# in-proj rope epilogues read the cos/sin table from LDS (staged once per phase) instead of global loads with full vmcnt drains
# speedup vs baseline: 1.0269x; 1.0017x over previous
; __global__ void __launch_bounds__(512, 2) fwd_kernel(Params prm) {
;     ...
;             if (F.bid == F.G - 1) { float* TAB = (float*)(ws + OFF_TAB);
;                 for (int i = F.tid; i < 64 * 32; i += 512) { const int pos = i >> 5, f = i & 31; float sn, cs; sincosf((float)pos * exp2f(-(float)f * (13.287712379549449f / 32.0f)), &sn, &cs); TAB[2 * i] = cs; TAB[2 * i + 1] = sn; } }
.Ltab_fill:
	v_readlane_b32 s0, v252, 1
	v_readlane_b32 s1, v252, 2
	v_mbcnt_lo_u32_b32 v1, -1, 0
	v_mbcnt_hi_u32_b32 v1, -1, v1
	v_readlane_b32 s2, v252, 7
	s_load_dwordx2 s[40:41], s[0:1], 0xc8
	s_nop 3
	s_lshl_b32 s2, s2, 6
	v_add_u32_e32 v1, s2, v1
	v_lshlrev_b32_e32 v0, 5, v1
	s_waitcnt lgkmcnt(0)
	s_add_u32 s40, s40, 0xf780000
	s_addc_u32 s41, s41, 0
	global_load_dwordx4 v[4:7], v0, s[40:41]
	global_load_dwordx4 v[8:11], v0, s[40:41] offset:16
	v_add_u32_e32 v1, 0x20000, v0
	s_waitcnt vmcnt(0)
	ds_write_b128 v1, v[4:7]
	ds_write_b128 v1, v[8:11] offset:16
	s_waitcnt lgkmcnt(0)
	s_barrier
	s_branch .Lnrm_ret

; __device__ __forceinline__ void convert_WA(const Ctx& F, int l) { convert_weights<false>(F, l); }
; __global__ void __launch_bounds__(512, 2) fwd_kernel(Params prm) {
;     ...
;         if (ph == 0) {
;             if (F.bid == F.G - 1) { float* TAB = (float*)(ws + OFF_TAB);
;                 for (int i = F.tid; i < 64 * 32; i += 512) { const int pos = i >> 5, f = i & 31; float sn, cs; sincosf((float)pos * exp2f(-(float)f * (13.287712379549449f / 32.0f)), &sn, &cs); TAB[2 * i] = cs; TAB[2 * i + 1] = sn; } }
;             mod_phase(F); __syncthreads(); convert_WA(F, 0); continue; }
;         if (ph == 1) { norm_phase<false, true>(F, MT, prm.in[0], prm.in[2], nullptr, nullptr, nullptr, nullptr, 0, nullptr, nullptr, prm.in[6], MOD, 1024, 0, RY); continue; }
;         const int l = (ph - 2) / 9, sp = (ph - 2) % 9;
;         const bool lastl = (l == 1);
;         bf16_t* Hl = l == 0 ? RY : RX; bf16_t* XRb = l == 0 ? RX : RY;
;         bf16_t* HF = Hl; bf16_t* Gb = XRb; bf16_t* H2 = RX;
;         const int Mg = lastl ? ML : MT;
;         const float* xres_lat = l == 0 ? prm.in[0] : prm.out; const float* xres_ctx = l == 0 ? prm.in[2] : ctxres;
;         const float* modl = MOD + (size_t)l * 5 * 6144;
;         switch (sp) {
;         case 0: { pg8::PlainOrder S; S.tm.init(MT, INW, F.G, F.bid); S.A = (const char*)Hl; S.B = (const char*)(ws + OFF_W + W_WIN); S.tsA = (size_t)256 * 1024 * 2; S.tsB = (size_t)256 * 1024 * 2; S.nt = 16;
.LBB0_76:
.LBB0_77:
	s_cmp_eq_u32 s72, 1
	s_cbranch_scc1 .Lnrm_ph1
	s_cmp_eq_u32 s72, 7
	s_cbranch_scc1 .Lnrm_sp5a
	s_cmp_eq_u32 s72, 16
	s_cbranch_scc1 .Lnrm_sp5b
	s_cmp_eq_u32 s72, 10
	s_cbranch_scc1 .Lnrm_sp8a
	s_cmp_eq_u32 s72, 19
	s_cbranch_scc1 .Lnrm_sp8b
	s_cmp_eq_u32 s72, 2
	s_cbranch_scc1 .Ltab_fill
	s_cmp_eq_u32 s72, 11
	s_cbranch_scc1 .Ltab_fill

; __device__ __forceinline__ unsigned cvt_pk_bf16(float lo, float hi) { unsigned r; asm volatile("v_cvt_pk_bf16_f32 %0, %1, %2" : "=v"(r) : "v"(lo), "v"(hi)); return r; }
;     template <int LDC> __device__ __forceinline__ void store_rope(const f32x4 (&acc)[2][2][4][2], bf16_t* base, int row0, int wc, int fq) const {
;         bf16_t* rp = base + (size_t)row0 * LDC; const int axis = wc >> 1, f0 = 16 * (wc & 1) + 4 * fq;
; #pragma unroll
;         for (int ai = 0; ai < 2; ++ai)
; #pragma unroll
;             for (int m = 0; m < 4; ++m) { const int row = row0 + ai * HALF + m * 16; bf16_t* rowp = rp + (size_t)(ai * HALF + m * 16) * LDC;
;                 const int t = row & (SEQ - 1), pos = axis ? (t & 63) : (t >> 6);
;                 f32x4 cs0 = *(const f32x4*)(TAB + (pos * 32 + f0) * 2), cs1 = *(const f32x4*)(TAB + (pos * 32 + f0) * 2 + 4);
;                 if (row >= ML) { cs0 = (f32x4){1.f, 0.f, 1.f, 0.f}; cs1 = cs0; }
; #pragma unroll
;                 for (int bj = 0; bj < 2; ++bj) { const f32x4 x1 = acc[ai][bj][m][0], x2 = acc[ai][bj][m][1];
;                     u32x4 w;
;                     w.x = cvt_pk_bf16(x1[0] * cs0[0] - x2[0] * cs0[1], x1[1] * cs0[2] - x2[1] * cs0[3]);
;                     w.y = cvt_pk_bf16(x1[2] * cs1[0] - x2[2] * cs1[1], x1[3] * cs1[2] - x2[3] * cs1[3]);
;                     w.z = cvt_pk_bf16(x2[0] * cs0[0] + x1[0] * cs0[1], x2[1] * cs0[2] + x1[1] * cs0[3]);
;                     w.w = cvt_pk_bf16(x2[2] * cs1[0] + x1[2] * cs1[1], x2[3] * cs1[2] + x1[3] * cs1[3]);
;                     *(u32x4*)(rowp + bj * HALF) = w; } }
.LBB0_595:
	s_andn2_b64 vcc, exec, s[18:19]
	s_cbranch_vccnz .LBB0_597
	v_ashrrev_i32_e32 v147, 31, v146
	v_ashrrev_i32_e32 v145, 31, v144
	s_lshr_b32 s18, s45, 6
	v_lshl_add_u64 v[130:131], v[146:147], 1, s[52:53]
	v_lshlrev_b64 v[132:133], 10, v[144:145]
	v_mov_b32_e32 v147, s18
	v_lshl_add_u64 v[148:149], v[130:131], 0, v[132:133]
	v_cndmask_b32_e64 v130, v159, v147, s[40:41]
	v_lshlrev_b32_e32 v130, 5, v130
	v_lshl_add_u32 v145, v167, 2, s39
	v_and_b32_e32 v130, 0x7e0, v130
	v_add_lshl_u32 v130, v130, v145, 1
	v_ashrrev_i32_e32 v131, 31, v130
	v_lshlrev_b32_e32 v130, 2, v130
	v_add_u32_e32 v130, 0x20000, v130
	ds_read_b128 v[176:179], v130 offset:16
	ds_read_b128 v[130:133], v130
	s_movk_i32 s18, 0x3fff
	v_cmp_lt_i32_e32 vcc, s18, v144
	v_mov_b32_e32 v161, v108
	s_movk_i32 s18, 0x3fef
	v_mov_b32_e32 v163, v56
	s_waitcnt lgkmcnt(0)
	v_cndmask_b32_e64 v153, v177, 0, vcc
	v_cndmask_b32_e64 v155, v131, 0, vcc
	v_cndmask_b32_e64 v154, v130, 1.0, vcc
	v_mov_b32_e32 v130, v126
	v_mov_b32_e32 v131, v122
	v_pk_mul_f32 v[130:131], v[130:131], v[154:155]
	v_cndmask_b32_e64 v133, v133, 0, vcc
	v_cndmask_b32_e64 v132, v132, 1.0, vcc
	v_sub_f32_e32 v160, v130, v131
	v_mov_b32_e32 v130, v127
	v_mov_b32_e32 v131, v123
	v_pk_mul_f32 v[130:131], v[130:131], v[132:133]
	v_cndmask_b32_e64 v152, v176, 1.0, vcc
	v_sub_f32_e32 v130, v130, v131
	v_cvt_pk_bf16_f32 v176, v160, v130
	v_mov_b32_e32 v130, v128
	v_mov_b32_e32 v131, v124
	v_pk_mul_f32 v[130:131], v[130:131], v[152:153]
	v_cndmask_b32_e64 v151, v179, 0, vcc
	v_cndmask_b32_e64 v150, v178, 1.0, vcc
	v_sub_f32_e32 v160, v130, v131
	v_mov_b32_e32 v130, v129
	v_mov_b32_e32 v131, v125
	v_pk_mul_f32 v[130:131], v[130:131], v[150:151]
	v_cmp_lt_i32_e32 vcc, s18, v144
	v_sub_f32_e32 v130, v130, v131
	v_cvt_pk_bf16_f32 v177, v160, v130
	v_mov_b32_e32 v130, v122
	v_mov_b32_e32 v131, v126
	v_pk_mul_f32 v[130:131], v[130:131], v[154:155]
	s_movk_i32 s18, 0x4000
	v_add_f32_e32 v160, v131, v130
	v_mov_b32_e32 v130, v123
	v_mov_b32_e32 v131, v127
	v_pk_mul_f32 v[130:131], v[130:131], v[132:133]
	s_nop 0
	v_add_f32_e32 v130, v131, v130
	v_cvt_pk_bf16_f32 v178, v160, v130
	v_mov_b32_e32 v130, v124
	v_mov_b32_e32 v131, v128
	v_pk_mul_f32 v[130:131], v[130:131], v[152:153]
	s_nop 0
	v_add_f32_e32 v160, v131, v130
	v_mov_b32_e32 v130, v125
	v_mov_b32_e32 v131, v129
	v_pk_mul_f32 v[130:131], v[130:131], v[150:151]
	s_nop 0
	v_add_f32_e32 v130, v131, v130
	v_cvt_pk_bf16_f32 v179, v160, v130
	v_mov_b32_e32 v130, v114
	v_mov_b32_e32 v131, v106
	v_pk_mul_f32 v[130:131], v[130:131], v[154:155]
	global_store_dwordx4 v[148:149], v[176:179], off sc1
	v_sub_f32_e32 v160, v130, v131
	v_mov_b32_e32 v130, v115
	v_mov_b32_e32 v131, v107
	v_pk_mul_f32 v[130:131], v[130:131], v[132:133]
	s_nop 0
	v_sub_f32_e32 v130, v130, v131
	v_cvt_pk_bf16_f32 v130, v160, v130
	v_mov_b32_e32 v160, v116
	v_pk_mul_f32 v[160:161], v[160:161], v[152:153]
	s_nop 0
	v_sub_f32_e32 v131, v160, v161
	v_mov_b32_e32 v160, v117
	v_mov_b32_e32 v161, v109
	v_pk_mul_f32 v[160:161], v[160:161], v[150:151]
	s_nop 0
	v_sub_f32_e32 v160, v160, v161
	v_cvt_pk_bf16_f32 v131, v131, v160
	v_mov_b32_e32 v160, v106
	v_mov_b32_e32 v161, v114
	v_pk_mul_f32 v[154:155], v[160:161], v[154:155]
	v_mov_b32_e32 v161, v90
	v_add_f32_e32 v160, v155, v154
	v_mov_b32_e32 v154, v107
	v_mov_b32_e32 v155, v115
	v_pk_mul_f32 v[132:133], v[154:155], v[132:133]
	v_mov_b32_e32 v154, v108
	v_mov_b32_e32 v155, v116
	v_pk_mul_f32 v[152:153], v[154:155], v[152:153]
	v_add_f32_e32 v132, v133, v132
	v_add_f32_e32 v133, v153, v152
	v_mov_b32_e32 v152, v109
	v_mov_b32_e32 v153, v117
	v_pk_mul_f32 v[150:151], v[152:153], v[150:151]
	v_cvt_pk_bf16_f32 v132, v160, v132
	v_mov_b32_e32 v154, v118
	v_add_f32_e32 v150, v151, v150
	v_cvt_pk_bf16_f32 v133, v133, v150
	global_store_dwordx4 v[148:149], v[130:133], off offset:256 sc1
	v_mov_b32_e32 v155, v110
	s_nop 0
	v_or_b32_e32 v130, 16, v144
	v_cndmask_b32_e64 v130, v130, v147, s[40:41]
	v_lshlrev_b32_e32 v130, 5, v130
	v_and_b32_e32 v130, 0x7e0, v130
	v_add_lshl_u32 v130, v130, v145, 1
	v_ashrrev_i32_e32 v131, 31, v130
	v_lshlrev_b32_e32 v130, 2, v130
	v_add_u32_e32 v130, 0x20000, v130
	ds_read_b128 v[176:179], v130 offset:16
	ds_read_b128 v[130:133], v130
	s_waitcnt lgkmcnt(1)
	v_cndmask_b32_e64 v151, v177, 0, vcc
	s_waitcnt lgkmcnt(0)
; __device__ __forceinline__ unsigned cvt_pk_bf16(float lo, float hi) { unsigned r; asm volatile("v_cvt_pk_bf16_f32 %0, %1, %2" : "=v"(r) : "v"(lo), "v"(hi)); return r; }
;     template <int LDC> __device__ __forceinline__ void store_rope(const f32x4 (&acc)[2][2][4][2], bf16_t* base, int row0, int wc, int fq) const {
;         bf16_t* rp = base + (size_t)row0 * LDC; const int axis = wc >> 1, f0 = 16 * (wc & 1) + 4 * fq;
; #pragma unroll
;         for (int ai = 0; ai < 2; ++ai)
; #pragma unroll
;             for (int m = 0; m < 4; ++m) { const int row = row0 + ai * HALF + m * 16; bf16_t* rowp = rp + (size_t)(ai * HALF + m * 16) * LDC;
;                 const int t = row & (SEQ - 1), pos = axis ? (t & 63) : (t >> 6);
;                 f32x4 cs0 = *(const f32x4*)(TAB + (pos * 32 + f0) * 2), cs1 = *(const f32x4*)(TAB + (pos * 32 + f0) * 2 + 4);
;                 if (row >= ML) { cs0 = (f32x4){1.f, 0.f, 1.f, 0.f}; cs1 = cs0; }
; #pragma unroll
;                 for (int bj = 0; bj < 2; ++bj) { const f32x4 x1 = acc[ai][bj][m][0], x2 = acc[ai][bj][m][1];
;                     u32x4 w;
;                     w.x = cvt_pk_bf16(x1[0] * cs0[0] - x2[0] * cs0[1], x1[1] * cs0[2] - x2[1] * cs0[3]);
;                     w.y = cvt_pk_bf16(x1[2] * cs1[0] - x2[2] * cs1[1], x1[3] * cs1[2] - x2[3] * cs1[3]);
;                     w.z = cvt_pk_bf16(x2[0] * cs0[0] + x1[0] * cs0[1], x2[1] * cs0[2] + x1[1] * cs0[3]);
;                     w.w = cvt_pk_bf16(x2[2] * cs1[0] + x1[2] * cs1[1], x2[3] * cs1[2] + x1[3] * cs1[3]);
;                     *(u32x4*)(rowp + bj * HALF) = w; } }
	v_cndmask_b32_e64 v153, v131, 0, vcc
	v_cndmask_b32_e64 v152, v130, 1.0, vcc
	v_pk_mul_f32 v[154:155], v[154:155], v[152:153]
	v_cndmask_b32_e64 v133, v133, 0, vcc
	v_cndmask_b32_e64 v132, v132, 1.0, vcc
	v_sub_f32_e32 v160, v154, v155
	v_mov_b32_e32 v154, v119
	v_mov_b32_e32 v155, v111
	v_pk_mul_f32 v[154:155], v[154:155], v[132:133]
	v_cndmask_b32_e64 v150, v176, 1.0, vcc
	v_sub_f32_e32 v154, v154, v155
	v_cvt_pk_bf16_f32 v176, v160, v154
	v_mov_b32_e32 v154, v120
	v_mov_b32_e32 v155, v112
	v_pk_mul_f32 v[154:155], v[154:155], v[150:151]
	v_cndmask_b32_e64 v131, v179, 0, vcc
	v_cndmask_b32_e64 v130, v178, 1.0, vcc
	v_sub_f32_e32 v160, v154, v155
	v_mov_b32_e32 v154, v121
	v_mov_b32_e32 v155, v113
	v_pk_mul_f32 v[154:155], v[154:155], v[130:131]
	s_nop 0
	v_sub_f32_e32 v154, v154, v155
	v_cvt_pk_bf16_f32 v177, v160, v154
	v_mov_b32_e32 v154, v110
	v_mov_b32_e32 v155, v118
	v_pk_mul_f32 v[154:155], v[154:155], v[152:153]
	s_nop 0
	v_add_f32_e32 v160, v155, v154
	v_mov_b32_e32 v154, v111
	v_mov_b32_e32 v155, v119
	v_pk_mul_f32 v[154:155], v[154:155], v[132:133]
	s_nop 0
	v_add_f32_e32 v154, v155, v154
	v_cvt_pk_bf16_f32 v178, v160, v154
	v_mov_b32_e32 v154, v112
	v_mov_b32_e32 v155, v120
	v_pk_mul_f32 v[154:155], v[154:155], v[150:151]
	s_nop 0
	v_add_f32_e32 v160, v155, v154
	v_mov_b32_e32 v154, v113
	v_mov_b32_e32 v155, v121
	v_pk_mul_f32 v[154:155], v[154:155], v[130:131]
	s_nop 0
	v_add_f32_e32 v154, v155, v154
	v_cvt_pk_bf16_f32 v179, v160, v154
	v_mov_b32_e32 v160, v98
	v_pk_mul_f32 v[160:161], v[160:161], v[152:153]
	v_add_co_u32_e32 v154, vcc, s18, v148
	v_sub_f32_e32 v162, v160, v161
	v_mov_b32_e32 v160, v99
	v_mov_b32_e32 v161, v91
	v_pk_mul_f32 v[160:161], v[160:161], v[132:133]
	v_addc_co_u32_e32 v155, vcc, 0, v149, vcc
	v_sub_f32_e32 v160, v160, v161
	global_store_dwordx4 v[154:155], v[176:179], off sc1
	v_mov_b32_e32 v161, v92
	s_movk_i32 s18, 0x3fdf
	v_cvt_pk_bf16_f32 v176, v162, v160
	v_mov_b32_e32 v160, v100
	v_pk_mul_f32 v[160:161], v[160:161], v[150:151]
	v_cmp_lt_i32_e32 vcc, s18, v144
	v_sub_f32_e32 v162, v160, v161
	v_mov_b32_e32 v160, v101
	v_mov_b32_e32 v161, v93
	v_pk_mul_f32 v[160:161], v[160:161], v[130:131]
	s_mov_b32 s18, 0x8000
	v_sub_f32_e32 v160, v160, v161
	v_cvt_pk_bf16_f32 v177, v162, v160
	v_mov_b32_e32 v160, v90
	v_mov_b32_e32 v161, v98
	v_pk_mul_f32 v[152:153], v[160:161], v[152:153]
	v_mov_b32_e32 v161, v74
	v_add_f32_e32 v160, v153, v152
	v_mov_b32_e32 v152, v91
	v_mov_b32_e32 v153, v99
	v_pk_mul_f32 v[132:133], v[152:153], v[132:133]
	s_nop 0
	v_add_f32_e32 v132, v133, v132
	v_cvt_pk_bf16_f32 v178, v160, v132
	v_mov_b32_e32 v132, v92
	v_mov_b32_e32 v133, v100
	v_pk_mul_f32 v[132:133], v[132:133], v[150:151]
	s_nop 0
	v_add_f32_e32 v150, v133, v132
	v_mov_b32_e32 v132, v93
	v_mov_b32_e32 v133, v101
	v_pk_mul_f32 v[130:131], v[132:133], v[130:131]
	s_nop 0
	v_add_f32_e32 v130, v131, v130
	v_cvt_pk_bf16_f32 v179, v150, v130
	v_or_b32_e32 v130, 32, v144
	v_cndmask_b32_e64 v130, v130, v147, s[40:41]
	v_lshlrev_b32_e32 v130, 5, v130
	v_and_b32_e32 v130, 0x7e0, v130
	v_add_lshl_u32 v130, v130, v145, 1
	v_ashrrev_i32_e32 v131, 31, v130
	global_store_dwordx4 v[154:155], v[176:179], off offset:256 sc1
	v_lshlrev_b32_e32 v130, 2, v130
	v_add_u32_e32 v130, 0x20000, v130
	ds_read_b128 v[176:179], v130 offset:16
	ds_read_b128 v[130:133], v130
	v_mov_b32_e32 v154, v102
	v_mov_b32_e32 v155, v94
	s_waitcnt lgkmcnt(1)
	v_cndmask_b32_e64 v151, v177, 0, vcc
	s_waitcnt lgkmcnt(0)
	v_cndmask_b32_e64 v153, v131, 0, vcc
	v_cndmask_b32_e64 v152, v130, 1.0, vcc
	v_pk_mul_f32 v[154:155], v[154:155], v[152:153]
	v_cndmask_b32_e64 v133, v133, 0, vcc
	v_cndmask_b32_e64 v132, v132, 1.0, vcc
	v_sub_f32_e32 v160, v154, v155
	v_mov_b32_e32 v154, v103
	v_mov_b32_e32 v155, v95
	v_pk_mul_f32 v[154:155], v[154:155], v[132:133]
	v_cndmask_b32_e64 v150, v176, 1.0, vcc
	v_sub_f32_e32 v154, v154, v155
	v_cvt_pk_bf16_f32 v176, v160, v154
	v_mov_b32_e32 v154, v104
	v_mov_b32_e32 v155, v96
	v_pk_mul_f32 v[154:155], v[154:155], v[150:151]
	v_cndmask_b32_e64 v131, v179, 0, vcc
	v_cndmask_b32_e64 v130, v178, 1.0, vcc
	v_sub_f32_e32 v160, v154, v155
	v_mov_b32_e32 v154, v105
	v_mov_b32_e32 v155, v97
	v_pk_mul_f32 v[154:155], v[154:155], v[130:131]
	s_nop 0
	v_sub_f32_e32 v154, v154, v155
	v_cvt_pk_bf16_f32 v177, v160, v154
	v_mov_b32_e32 v154, v94
	v_mov_b32_e32 v155, v102
	v_pk_mul_f32 v[154:155], v[154:155], v[152:153]
	s_nop 0
	v_add_f32_e32 v160, v155, v154
	v_mov_b32_e32 v154, v95
	v_mov_b32_e32 v155, v103
	v_pk_mul_f32 v[154:155], v[154:155], v[132:133]
	s_nop 0
	v_add_f32_e32 v154, v155, v154
	v_cvt_pk_bf16_f32 v178, v160, v154
	v_mov_b32_e32 v154, v96
	v_mov_b32_e32 v155, v104
	v_pk_mul_f32 v[154:155], v[154:155], v[150:151]
	s_nop 0
	v_add_f32_e32 v160, v155, v154
	v_mov_b32_e32 v154, v97
	v_mov_b32_e32 v155, v105
	v_pk_mul_f32 v[154:155], v[154:155], v[130:131]
	s_nop 0
	v_add_f32_e32 v154, v155, v154
	v_cvt_pk_bf16_f32 v179, v160, v154
	v_mov_b32_e32 v160, v82
	v_pk_mul_f32 v[160:161], v[160:161], v[152:153]
	v_add_co_u32_e32 v154, vcc, s18, v148
	v_sub_f32_e32 v162, v160, v161
	v_mov_b32_e32 v160, v83
	v_mov_b32_e32 v161, v75
	v_pk_mul_f32 v[160:161], v[160:161], v[132:133]
	v_addc_co_u32_e32 v155, vcc, 0, v149, vcc
	v_sub_f32_e32 v160, v160, v161
	global_store_dwordx4 v[154:155], v[176:179], off sc1
	v_mov_b32_e32 v161, v76
	s_movk_i32 s18, 0x3fcf
	v_cvt_pk_bf16_f32 v176, v162, v160
	v_mov_b32_e32 v160, v84
	v_pk_mul_f32 v[160:161], v[160:161], v[150:151]
	v_cmp_lt_i32_e32 vcc, s18, v144
	v_sub_f32_e32 v162, v160, v161
	v_mov_b32_e32 v160, v85
	v_mov_b32_e32 v161, v77
	v_pk_mul_f32 v[160:161], v[160:161], v[130:131]
	s_add_i32 s18, s45, 0x80
	v_sub_f32_e32 v160, v160, v161
	v_cvt_pk_bf16_f32 v177, v162, v160
	v_mov_b32_e32 v160, v74
	v_mov_b32_e32 v161, v82
	v_pk_mul_f32 v[152:153], v[160:161], v[152:153]
	v_mov_b32_e32 v161, v66
	v_add_f32_e32 v160, v153, v152
	v_mov_b32_e32 v152, v75
	v_mov_b32_e32 v153, v83
	v_pk_mul_f32 v[132:133], v[152:153], v[132:133]
	s_lshr_b32 s18, s18, 6
	v_add_f32_e32 v132, v133, v132
	v_cvt_pk_bf16_f32 v178, v160, v132
	v_mov_b32_e32 v132, v76
	v_mov_b32_e32 v133, v84
	v_pk_mul_f32 v[132:133], v[132:133], v[150:151]
	v_mov_b32_e32 v160, v70
	v_add_f32_e32 v150, v133, v132
	v_mov_b32_e32 v132, v77
	v_mov_b32_e32 v133, v85
	v_pk_mul_f32 v[130:131], v[132:133], v[130:131]
	v_mov_b32_e32 v162, v48
	v_add_f32_e32 v130, v131, v130
	v_cvt_pk_bf16_f32 v179, v150, v130
	v_or_b32_e32 v130, 48, v144
	v_cndmask_b32_e64 v130, v130, v147, s[40:41]
	v_lshlrev_b32_e32 v130, 5, v130
	v_and_b32_e32 v130, 0x7e0, v130
	v_add_lshl_u32 v130, v130, v145, 1
	v_ashrrev_i32_e32 v131, 31, v130
	global_store_dwordx4 v[154:155], v[176:179], off offset:256 sc1
	v_lshlrev_b32_e32 v130, 2, v130
	v_add_u32_e32 v130, 0x20000, v130
	ds_read_b128 v[176:179], v130 offset:16
	ds_read_b128 v[130:133], v130
	v_mov_b32_e32 v154, v86
	v_mov_b32_e32 v155, v78
	s_waitcnt lgkmcnt(1)
; __device__ __forceinline__ unsigned cvt_pk_bf16(float lo, float hi) { unsigned r; asm volatile("v_cvt_pk_bf16_f32 %0, %1, %2" : "=v"(r) : "v"(lo), "v"(hi)); return r; }
;     template <int LDC> __device__ __forceinline__ void store_rope(const f32x4 (&acc)[2][2][4][2], bf16_t* base, int row0, int wc, int fq) const {
;         bf16_t* rp = base + (size_t)row0 * LDC; const int axis = wc >> 1, f0 = 16 * (wc & 1) + 4 * fq;
; #pragma unroll
;         for (int ai = 0; ai < 2; ++ai)
; #pragma unroll
;             for (int m = 0; m < 4; ++m) { const int row = row0 + ai * HALF + m * 16; bf16_t* rowp = rp + (size_t)(ai * HALF + m * 16) * LDC;
;                 const int t = row & (SEQ - 1), pos = axis ? (t & 63) : (t >> 6);
;                 f32x4 cs0 = *(const f32x4*)(TAB + (pos * 32 + f0) * 2), cs1 = *(const f32x4*)(TAB + (pos * 32 + f0) * 2 + 4);
;                 if (row >= ML) { cs0 = (f32x4){1.f, 0.f, 1.f, 0.f}; cs1 = cs0; }
; #pragma unroll
;                 for (int bj = 0; bj < 2; ++bj) { const f32x4 x1 = acc[ai][bj][m][0], x2 = acc[ai][bj][m][1];
;                     u32x4 w;
;                     w.x = cvt_pk_bf16(x1[0] * cs0[0] - x2[0] * cs0[1], x1[1] * cs0[2] - x2[1] * cs0[3]);
;                     w.y = cvt_pk_bf16(x1[2] * cs1[0] - x2[2] * cs1[1], x1[3] * cs1[2] - x2[3] * cs1[3]);
;                     w.z = cvt_pk_bf16(x2[0] * cs0[0] + x1[0] * cs0[1], x2[1] * cs0[2] + x1[1] * cs0[3]);
;                     w.w = cvt_pk_bf16(x2[2] * cs1[0] + x1[2] * cs1[1], x2[3] * cs1[2] + x1[3] * cs1[3]);
;                     *(u32x4*)(rowp + bj * HALF) = w; } }
	v_cndmask_b32_e64 v151, v177, 0, vcc
	s_waitcnt lgkmcnt(0)
	v_cndmask_b32_e64 v153, v131, 0, vcc
	v_cndmask_b32_e64 v152, v130, 1.0, vcc
	v_pk_mul_f32 v[154:155], v[154:155], v[152:153]
	v_cndmask_b32_e64 v133, v133, 0, vcc
	v_cndmask_b32_e64 v132, v132, 1.0, vcc
	v_sub_f32_e32 v147, v154, v155
	v_mov_b32_e32 v154, v87
	v_mov_b32_e32 v155, v79
	v_pk_mul_f32 v[154:155], v[154:155], v[132:133]
	v_cndmask_b32_e64 v150, v176, 1.0, vcc
	v_sub_f32_e32 v154, v154, v155
	v_cvt_pk_bf16_f32 v176, v147, v154
	v_mov_b32_e32 v154, v88
	v_mov_b32_e32 v155, v80
	v_pk_mul_f32 v[154:155], v[154:155], v[150:151]
	v_cndmask_b32_e64 v131, v179, 0, vcc
	v_cndmask_b32_e64 v130, v178, 1.0, vcc
	v_sub_f32_e32 v147, v154, v155
	v_mov_b32_e32 v154, v89
	v_mov_b32_e32 v155, v81
	v_pk_mul_f32 v[154:155], v[154:155], v[130:131]
	v_pk_mul_f32 v[160:161], v[160:161], v[152:153]
	v_sub_f32_e32 v154, v154, v155
	v_cvt_pk_bf16_f32 v177, v147, v154
	v_mov_b32_e32 v154, v78
	v_mov_b32_e32 v155, v86
	v_pk_mul_f32 v[154:155], v[154:155], v[152:153]
	s_nop 0
	v_add_f32_e32 v147, v155, v154
	v_mov_b32_e32 v154, v79
	v_mov_b32_e32 v155, v87
	v_pk_mul_f32 v[154:155], v[154:155], v[132:133]
	s_nop 0
	v_add_f32_e32 v154, v155, v154
	v_cvt_pk_bf16_f32 v178, v147, v154
	v_mov_b32_e32 v154, v80
	v_mov_b32_e32 v155, v88
	v_pk_mul_f32 v[154:155], v[154:155], v[150:151]
	s_nop 0
	v_add_f32_e32 v147, v155, v154
	v_mov_b32_e32 v154, v81
	v_mov_b32_e32 v155, v89
	v_pk_mul_f32 v[154:155], v[154:155], v[130:131]
	s_nop 0
	v_add_f32_e32 v154, v155, v154
	v_cvt_pk_bf16_f32 v179, v147, v154
	v_sub_f32_e32 v147, v160, v161
	v_mov_b32_e32 v160, v71
	v_mov_b32_e32 v161, v67
	v_add_co_u32_e32 v154, vcc, s95, v148
	v_pk_mul_f32 v[160:161], v[160:161], v[132:133]
	s_nop 0
	v_addc_co_u32_e32 v155, vcc, 0, v149, vcc
	v_sub_f32_e32 v160, v160, v161
	global_store_dwordx4 v[154:155], v[176:179], off sc1
	v_mov_b32_e32 v161, v68
	s_nop 0
	v_cvt_pk_bf16_f32 v176, v147, v160
	v_mov_b32_e32 v160, v72
	v_pk_mul_f32 v[160:161], v[160:161], v[150:151]
	s_nop 0
	v_sub_f32_e32 v147, v160, v161
	v_mov_b32_e32 v160, v73
	v_mov_b32_e32 v161, v69
	v_pk_mul_f32 v[160:161], v[160:161], v[130:131]
	s_nop 0
	v_sub_f32_e32 v160, v160, v161
	v_cvt_pk_bf16_f32 v177, v147, v160
	v_mov_b32_e32 v160, v66
	v_mov_b32_e32 v161, v70
	v_pk_mul_f32 v[152:153], v[160:161], v[152:153]
	v_mov_b32_e32 v160, v50
	v_add_f32_e32 v147, v153, v152
	v_mov_b32_e32 v152, v67
	v_mov_b32_e32 v153, v71
	v_pk_mul_f32 v[132:133], v[152:153], v[132:133]
	v_mov_b32_e32 v161, v42
	v_add_f32_e32 v132, v133, v132
	v_cvt_pk_bf16_f32 v178, v147, v132
	v_mov_b32_e32 v132, v68
	v_mov_b32_e32 v133, v72
	v_pk_mul_f32 v[132:133], v[132:133], v[150:151]
	s_nop 0
	v_add_f32_e32 v147, v133, v132
	v_mov_b32_e32 v132, v69
	v_mov_b32_e32 v133, v73
	v_pk_mul_f32 v[130:131], v[132:133], v[130:131]
	s_nop 0
	v_add_f32_e32 v130, v131, v130
	v_cvt_pk_bf16_f32 v179, v147, v130
	v_mov_b32_e32 v130, s18
	v_cndmask_b32_e64 v130, v159, v130, s[40:41]
	v_lshlrev_b32_e32 v130, 5, v130
	v_and_b32_e32 v130, 0x7e0, v130
	v_add_lshl_u32 v130, v130, v145, 1
	v_ashrrev_i32_e32 v131, 31, v130
	global_store_dwordx4 v[154:155], v[176:179], off offset:256 sc1
	v_lshlrev_b32_e32 v130, 2, v130
	v_add_u32_e32 v130, 0x20000, v130
	ds_read_b128 v[176:179], v130 offset:16
	ds_read_b128 v[130:133], v130
	s_movk_i32 s18, 0x3f7f
	v_cmp_lt_i32_e32 vcc, s18, v144
	v_mov_b32_e32 v154, v62
	v_mov_b32_e32 v155, v58
	s_mov_b32 s18, 0x20000
	s_waitcnt lgkmcnt(1)
	v_cndmask_b32_e64 v151, v177, 0, vcc
	s_waitcnt lgkmcnt(0)
	v_cndmask_b32_e64 v153, v131, 0, vcc
	v_cndmask_b32_e64 v152, v130, 1.0, vcc
	v_pk_mul_f32 v[154:155], v[154:155], v[152:153]
	v_cndmask_b32_e64 v133, v133, 0, vcc
	v_cndmask_b32_e64 v132, v132, 1.0, vcc
	v_sub_f32_e32 v147, v154, v155
	v_mov_b32_e32 v154, v63
	v_mov_b32_e32 v155, v59
	v_pk_mul_f32 v[154:155], v[154:155], v[132:133]
	v_cndmask_b32_e64 v150, v176, 1.0, vcc
	v_sub_f32_e32 v154, v154, v155
	v_cvt_pk_bf16_f32 v176, v147, v154
	v_mov_b32_e32 v154, v64
	v_mov_b32_e32 v155, v60
	v_pk_mul_f32 v[154:155], v[154:155], v[150:151]
	v_cndmask_b32_e64 v131, v179, 0, vcc
	v_cndmask_b32_e64 v130, v178, 1.0, vcc
	v_sub_f32_e32 v147, v154, v155
	v_mov_b32_e32 v154, v65
	v_mov_b32_e32 v155, v61
	v_pk_mul_f32 v[154:155], v[154:155], v[130:131]
	v_pk_mul_f32 v[160:161], v[160:161], v[152:153]
	v_sub_f32_e32 v154, v154, v155
	v_cvt_pk_bf16_f32 v177, v147, v154
	v_mov_b32_e32 v154, v58
	v_mov_b32_e32 v155, v62
	v_pk_mul_f32 v[154:155], v[154:155], v[152:153]
	s_nop 0
	v_add_f32_e32 v147, v155, v154
	v_mov_b32_e32 v154, v59
	v_mov_b32_e32 v155, v63
	v_pk_mul_f32 v[154:155], v[154:155], v[132:133]
	s_nop 0
	v_add_f32_e32 v154, v155, v154
	v_cvt_pk_bf16_f32 v178, v147, v154
	v_mov_b32_e32 v154, v60
	v_mov_b32_e32 v155, v64
	v_pk_mul_f32 v[154:155], v[154:155], v[150:151]
	s_nop 0
	v_add_f32_e32 v147, v155, v154
	v_mov_b32_e32 v154, v61
	v_mov_b32_e32 v155, v65
	v_pk_mul_f32 v[154:155], v[154:155], v[130:131]
	s_nop 0
	v_add_f32_e32 v154, v155, v154
	v_cvt_pk_bf16_f32 v179, v147, v154
	v_sub_f32_e32 v147, v160, v161
	v_mov_b32_e32 v160, v51
	v_mov_b32_e32 v161, v43
	v_add_co_u32_e32 v154, vcc, s18, v148
	v_pk_mul_f32 v[160:161], v[160:161], v[132:133]
	s_nop 0
	v_addc_co_u32_e32 v155, vcc, 0, v149, vcc
	v_sub_f32_e32 v160, v160, v161
	global_store_dwordx4 v[154:155], v[176:179], off sc1
	v_mov_b32_e32 v161, v44
	s_movk_i32 s18, 0x3f6f
	v_cvt_pk_bf16_f32 v176, v147, v160
	v_mov_b32_e32 v160, v52
	v_pk_mul_f32 v[160:161], v[160:161], v[150:151]
	v_cmp_lt_i32_e32 vcc, s18, v144
	v_sub_f32_e32 v147, v160, v161
	v_mov_b32_e32 v160, v53
	v_mov_b32_e32 v161, v45
	v_pk_mul_f32 v[160:161], v[160:161], v[130:131]
	s_movk_i32 s18, 0x3f5f
	v_sub_f32_e32 v160, v160, v161
	v_cvt_pk_bf16_f32 v177, v147, v160
	v_mov_b32_e32 v160, v42
	v_mov_b32_e32 v161, v50
	v_pk_mul_f32 v[152:153], v[160:161], v[152:153]
	s_nop 0
	v_add_f32_e32 v147, v153, v152
	v_mov_b32_e32 v152, v43
	v_mov_b32_e32 v153, v51
	v_pk_mul_f32 v[132:133], v[152:153], v[132:133]
	s_nop 0
	v_add_f32_e32 v132, v133, v132
	v_cvt_pk_bf16_f32 v178, v147, v132
	v_mov_b32_e32 v132, v44
	v_mov_b32_e32 v133, v52
	v_pk_mul_f32 v[132:133], v[132:133], v[150:151]
	s_nop 0
	v_add_f32_e32 v147, v133, v132
	v_mov_b32_e32 v132, v45
	v_mov_b32_e32 v133, v53
	v_pk_mul_f32 v[130:131], v[132:133], v[130:131]
	s_nop 0
	v_add_f32_e32 v130, v131, v130
	v_cvt_pk_bf16_f32 v179, v147, v130
	v_add_u32_e32 v130, 0x90, v144
	v_lshrrev_b32_e32 v131, 6, v130
	v_cndmask_b32_e64 v130, v130, v131, s[40:41]
	v_lshlrev_b32_e32 v130, 5, v130
	v_and_b32_e32 v130, 0x7e0, v130
	v_add_lshl_u32 v130, v130, v145, 1
	v_ashrrev_i32_e32 v131, 31, v130
	global_store_dwordx4 v[154:155], v[176:179], off offset:256 sc1
	v_lshlrev_b32_e32 v150, 2, v130
	v_add_u32_e32 v150, 0x20000, v150
	ds_read_b128 v[130:133], v150 offset:16
	ds_read_b128 v[150:153], v150
	s_waitcnt lgkmcnt(1)
; __device__ __forceinline__ unsigned cvt_pk_bf16(float lo, float hi) { unsigned r; asm volatile("v_cvt_pk_bf16_f32 %0, %1, %2" : "=v"(r) : "v"(lo), "v"(hi)); return r; }
;     template <int LDC> __device__ __forceinline__ void store_rope(const f32x4 (&acc)[2][2][4][2], bf16_t* base, int row0, int wc, int fq) const {
;         bf16_t* rp = base + (size_t)row0 * LDC; const int axis = wc >> 1, f0 = 16 * (wc & 1) + 4 * fq;
; #pragma unroll
;         for (int ai = 0; ai < 2; ++ai)
; #pragma unroll
;             for (int m = 0; m < 4; ++m) { const int row = row0 + ai * HALF + m * 16; bf16_t* rowp = rp + (size_t)(ai * HALF + m * 16) * LDC;
;                 const int t = row & (SEQ - 1), pos = axis ? (t & 63) : (t >> 6);
;                 f32x4 cs0 = *(const f32x4*)(TAB + (pos * 32 + f0) * 2), cs1 = *(const f32x4*)(TAB + (pos * 32 + f0) * 2 + 4);
;                 if (row >= ML) { cs0 = (f32x4){1.f, 0.f, 1.f, 0.f}; cs1 = cs0; }
; #pragma unroll
;                 for (int bj = 0; bj < 2; ++bj) { const f32x4 x1 = acc[ai][bj][m][0], x2 = acc[ai][bj][m][1];
;                     u32x4 w;
;                     w.x = cvt_pk_bf16(x1[0] * cs0[0] - x2[0] * cs0[1], x1[1] * cs0[2] - x2[1] * cs0[3]);
;                     w.y = cvt_pk_bf16(x1[2] * cs1[0] - x2[2] * cs1[1], x1[3] * cs1[2] - x2[3] * cs1[3]);
;                     w.z = cvt_pk_bf16(x2[0] * cs0[0] + x1[0] * cs0[1], x2[1] * cs0[2] + x1[1] * cs0[3]);
;                     w.w = cvt_pk_bf16(x2[2] * cs1[0] + x1[2] * cs1[1], x2[3] * cs1[2] + x1[3] * cs1[3]);
;                     *(u32x4*)(rowp + bj * HALF) = w; } }
	v_cndmask_b32_e64 v161, v131, 0, vcc
	s_waitcnt lgkmcnt(0)
	v_cndmask_b32_e64 v151, v151, 0, vcc
	v_cndmask_b32_e64 v150, v150, 1.0, vcc
	v_cndmask_b32_e64 v160, v130, 1.0, vcc
	v_mov_b32_e32 v130, v54
	v_mov_b32_e32 v131, v46
	v_pk_mul_f32 v[130:131], v[130:131], v[150:151]
	v_cndmask_b32_e64 v153, v153, 0, vcc
	v_cndmask_b32_e64 v152, v152, 1.0, vcc
	v_cndmask_b32_e64 v154, v132, 1.0, vcc
	v_sub_f32_e32 v132, v130, v131
	v_mov_b32_e32 v130, v55
	v_mov_b32_e32 v131, v47
	v_pk_mul_f32 v[130:131], v[130:131], v[152:153]
	v_cndmask_b32_e64 v155, v133, 0, vcc
	v_sub_f32_e32 v130, v130, v131
	v_cvt_pk_bf16_f32 v130, v132, v130
	v_mov_b32_e32 v132, v56
	v_mov_b32_e32 v133, v48
	v_pk_mul_f32 v[132:133], v[132:133], v[160:161]
	v_pk_mul_f32 v[162:163], v[162:163], v[160:161]
	v_sub_f32_e32 v131, v132, v133
	v_mov_b32_e32 v132, v57
	v_mov_b32_e32 v133, v49
	v_pk_mul_f32 v[132:133], v[132:133], v[154:155]
	s_nop 0
	v_sub_f32_e32 v132, v132, v133
	v_cvt_pk_bf16_f32 v131, v131, v132
	v_mov_b32_e32 v132, v46
	v_mov_b32_e32 v133, v54
	v_pk_mul_f32 v[132:133], v[132:133], v[150:151]
	s_nop 0
	v_add_f32_e32 v147, v133, v132
	v_mov_b32_e32 v132, v47
	v_mov_b32_e32 v133, v55
	v_pk_mul_f32 v[132:133], v[132:133], v[152:153]
	s_nop 0
	v_add_f32_e32 v132, v133, v132
	v_add_f32_e32 v133, v163, v162
	v_mov_b32_e32 v162, v49
	v_mov_b32_e32 v163, v57
	v_pk_mul_f32 v[162:163], v[162:163], v[154:155]
	v_cvt_pk_bf16_f32 v132, v147, v132
	s_nop 0
	v_add_f32_e32 v147, v163, v162
	v_add_co_u32_e32 v162, vcc, s83, v148
	v_cvt_pk_bf16_f32 v133, v133, v147
	s_nop 1
	v_addc_co_u32_e32 v163, vcc, 0, v149, vcc
	global_store_dwordx4 v[162:163], v[130:133], off sc1
	v_cmp_lt_i32_e32 vcc, s18, v144
	s_mov_b32 s18, 0x28000
	v_mov_b32_e32 v130, v34
	v_mov_b32_e32 v131, v24
	v_pk_mul_f32 v[130:131], v[130:131], v[150:151]
	v_mov_b32_e32 v133, v26
	v_sub_f32_e32 v132, v130, v131
	v_mov_b32_e32 v130, v35
	v_mov_b32_e32 v131, v25
	v_pk_mul_f32 v[130:131], v[130:131], v[152:153]
	s_nop 0
	v_sub_f32_e32 v130, v130, v131
	v_cvt_pk_bf16_f32 v130, v132, v130
	v_mov_b32_e32 v132, v36
	v_pk_mul_f32 v[132:133], v[132:133], v[160:161]
	s_nop 0
	v_sub_f32_e32 v131, v132, v133
	v_mov_b32_e32 v132, v37
	v_mov_b32_e32 v133, v27
	v_pk_mul_f32 v[132:133], v[132:133], v[154:155]
	s_nop 0
	v_sub_f32_e32 v132, v132, v133
	v_cvt_pk_bf16_f32 v131, v131, v132
	v_mov_b32_e32 v132, v24
	v_mov_b32_e32 v133, v34
	v_pk_mul_f32 v[132:133], v[132:133], v[150:151]
	v_mov_b32_e32 v150, v26
	v_add_f32_e32 v147, v133, v132
	v_mov_b32_e32 v132, v25
	v_mov_b32_e32 v133, v35
	v_mov_b32_e32 v151, v36
	v_pk_mul_f32 v[132:133], v[132:133], v[152:153]
	v_pk_mul_f32 v[150:151], v[150:151], v[160:161]
	v_add_f32_e32 v132, v133, v132
	v_add_f32_e32 v133, v151, v150
	v_mov_b32_e32 v150, v27
	v_mov_b32_e32 v151, v37
	v_pk_mul_f32 v[150:151], v[150:151], v[154:155]
	v_cvt_pk_bf16_f32 v132, v147, v132
	s_nop 0
	v_add_f32_e32 v147, v151, v150
	v_cvt_pk_bf16_f32 v133, v133, v147
	global_store_dwordx4 v[162:163], v[130:133], off offset:256 sc1
	v_mov_b32_e32 v162, v30
	v_mov_b32_e32 v163, v40
	v_add_u32_e32 v130, 0xa0, v144
	v_lshrrev_b32_e32 v131, 6, v130
	v_cndmask_b32_e64 v130, v130, v131, s[40:41]
	v_lshlrev_b32_e32 v130, 5, v130
	v_and_b32_e32 v130, 0x7e0, v130
	v_add_lshl_u32 v130, v130, v145, 1
	v_ashrrev_i32_e32 v131, 31, v130
	v_lshlrev_b32_e32 v150, 2, v130
	v_add_u32_e32 v150, 0x20000, v150
	ds_read_b128 v[130:133], v150 offset:16
	ds_read_b128 v[150:153], v150
	s_waitcnt lgkmcnt(1)
	v_cndmask_b32_e64 v161, v131, 0, vcc
	s_waitcnt lgkmcnt(0)
; __device__ __forceinline__ unsigned cvt_pk_bf16(float lo, float hi) { unsigned r; asm volatile("v_cvt_pk_bf16_f32 %0, %1, %2" : "=v"(r) : "v"(lo), "v"(hi)); return r; }
;     template <int LDC> __device__ __forceinline__ void store_rope(const f32x4 (&acc)[2][2][4][2], bf16_t* base, int row0, int wc, int fq) const {
;         bf16_t* rp = base + (size_t)row0 * LDC; const int axis = wc >> 1, f0 = 16 * (wc & 1) + 4 * fq;
; #pragma unroll
;         for (int ai = 0; ai < 2; ++ai)
; #pragma unroll
;             for (int m = 0; m < 4; ++m) { const int row = row0 + ai * HALF + m * 16; bf16_t* rowp = rp + (size_t)(ai * HALF + m * 16) * LDC;
;                 const int t = row & (SEQ - 1), pos = axis ? (t & 63) : (t >> 6);
;                 f32x4 cs0 = *(const f32x4*)(TAB + (pos * 32 + f0) * 2), cs1 = *(const f32x4*)(TAB + (pos * 32 + f0) * 2 + 4);
;                 if (row >= ML) { cs0 = (f32x4){1.f, 0.f, 1.f, 0.f}; cs1 = cs0; }
; #pragma unroll
;                 for (int bj = 0; bj < 2; ++bj) { const f32x4 x1 = acc[ai][bj][m][0], x2 = acc[ai][bj][m][1];
;                     u32x4 w;
;                     w.x = cvt_pk_bf16(x1[0] * cs0[0] - x2[0] * cs0[1], x1[1] * cs0[2] - x2[1] * cs0[3]);
;                     w.y = cvt_pk_bf16(x1[2] * cs1[0] - x2[2] * cs1[1], x1[3] * cs1[2] - x2[3] * cs1[3]);
;                     w.z = cvt_pk_bf16(x2[0] * cs0[0] + x1[0] * cs0[1], x2[1] * cs0[2] + x1[1] * cs0[3]);
;                     w.w = cvt_pk_bf16(x2[2] * cs1[0] + x1[2] * cs1[1], x2[3] * cs1[2] + x1[3] * cs1[3]);
;                     *(u32x4*)(rowp + bj * HALF) = w; } }
	v_cndmask_b32_e64 v151, v151, 0, vcc
	v_cndmask_b32_e64 v150, v150, 1.0, vcc
	v_cndmask_b32_e64 v160, v130, 1.0, vcc
	v_mov_b32_e32 v130, v38
	v_mov_b32_e32 v131, v28
	v_pk_mul_f32 v[130:131], v[130:131], v[150:151]
	v_cndmask_b32_e64 v153, v153, 0, vcc
	v_cndmask_b32_e64 v152, v152, 1.0, vcc
	v_cndmask_b32_e64 v154, v132, 1.0, vcc
	v_sub_f32_e32 v132, v130, v131
	v_mov_b32_e32 v130, v39
	v_mov_b32_e32 v131, v29
	v_pk_mul_f32 v[130:131], v[130:131], v[152:153]
	v_cndmask_b32_e64 v155, v133, 0, vcc
	v_sub_f32_e32 v130, v130, v131
	v_cvt_pk_bf16_f32 v130, v132, v130
	v_mov_b32_e32 v132, v40
	v_mov_b32_e32 v133, v30
	v_pk_mul_f32 v[132:133], v[132:133], v[160:161]
	v_pk_mul_f32 v[162:163], v[162:163], v[160:161]
	v_sub_f32_e32 v131, v132, v133
	v_mov_b32_e32 v132, v41
	v_mov_b32_e32 v133, v31
	v_pk_mul_f32 v[132:133], v[132:133], v[154:155]
	s_nop 0
	v_sub_f32_e32 v132, v132, v133
	v_cvt_pk_bf16_f32 v131, v131, v132
	v_mov_b32_e32 v132, v28
	v_mov_b32_e32 v133, v38
	v_pk_mul_f32 v[132:133], v[132:133], v[150:151]
	s_nop 0
	v_add_f32_e32 v147, v133, v132
	v_mov_b32_e32 v132, v29
	v_mov_b32_e32 v133, v39
	v_pk_mul_f32 v[132:133], v[132:133], v[152:153]
	s_nop 0
	v_add_f32_e32 v132, v133, v132
	v_add_f32_e32 v133, v163, v162
	v_mov_b32_e32 v162, v31
	v_mov_b32_e32 v163, v41
	v_pk_mul_f32 v[162:163], v[162:163], v[154:155]
	v_cvt_pk_bf16_f32 v132, v147, v132
	s_nop 0
	v_add_f32_e32 v147, v163, v162
	v_add_co_u32_e32 v162, vcc, s18, v148
	v_cvt_pk_bf16_f32 v133, v133, v147
	s_movk_i32 s18, 0x3f4f
	s_nop 0
	v_addc_co_u32_e32 v163, vcc, 0, v149, vcc
	global_store_dwordx4 v[162:163], v[130:133], off sc1
	v_cmp_lt_i32_e32 vcc, s18, v144
	s_mov_b32 s18, 0x2c000
	v_mov_b32_e32 v130, v16
	v_mov_b32_e32 v131, v8
	v_pk_mul_f32 v[130:131], v[130:131], v[150:151]
	v_mov_b32_e32 v133, v10
	v_sub_f32_e32 v132, v130, v131
	v_mov_b32_e32 v130, v17
	v_mov_b32_e32 v131, v9
	v_pk_mul_f32 v[130:131], v[130:131], v[152:153]
	s_nop 0
	v_sub_f32_e32 v130, v130, v131
	v_cvt_pk_bf16_f32 v130, v132, v130
	v_mov_b32_e32 v132, v18
	v_pk_mul_f32 v[132:133], v[132:133], v[160:161]
	s_nop 0
	v_sub_f32_e32 v131, v132, v133
	v_mov_b32_e32 v132, v19
	v_mov_b32_e32 v133, v11
	v_pk_mul_f32 v[132:133], v[132:133], v[154:155]
	s_nop 0
	v_sub_f32_e32 v132, v132, v133
	v_cvt_pk_bf16_f32 v131, v131, v132
	v_mov_b32_e32 v132, v8
	v_mov_b32_e32 v133, v16
	v_pk_mul_f32 v[132:133], v[132:133], v[150:151]
	v_mov_b32_e32 v150, v10
	v_add_f32_e32 v147, v133, v132
	v_mov_b32_e32 v132, v9
	v_mov_b32_e32 v133, v17
	v_mov_b32_e32 v151, v18
	v_pk_mul_f32 v[132:133], v[132:133], v[152:153]
	v_pk_mul_f32 v[150:151], v[150:151], v[160:161]
	v_add_f32_e32 v132, v133, v132
	v_add_f32_e32 v133, v151, v150
	v_mov_b32_e32 v150, v11
	v_mov_b32_e32 v151, v19
	v_pk_mul_f32 v[150:151], v[150:151], v[154:155]
	v_cvt_pk_bf16_f32 v132, v147, v132
	s_nop 0
	v_add_f32_e32 v147, v151, v150
	v_cvt_pk_bf16_f32 v133, v133, v147
	global_store_dwordx4 v[162:163], v[130:133], off offset:256 sc1
	v_mov_b32_e32 v162, v14
	v_mov_b32_e32 v163, v22
	v_add_u32_e32 v130, 0xb0, v144
	v_lshrrev_b32_e32 v131, 6, v130
	v_cndmask_b32_e64 v130, v130, v131, s[40:41]
	v_lshlrev_b32_e32 v130, 5, v130
	v_and_b32_e32 v130, 0x7e0, v130
	v_add_lshl_u32 v130, v130, v145, 1
	v_ashrrev_i32_e32 v131, 31, v130
	v_lshlrev_b32_e32 v150, 2, v130
	v_add_u32_e32 v150, 0x20000, v150
	ds_read_b128 v[130:133], v150 offset:16
	ds_read_b128 v[150:153], v150
	s_waitcnt lgkmcnt(1)
	v_cndmask_b32_e64 v161, v131, 0, vcc
	s_waitcnt lgkmcnt(0)
	v_cndmask_b32_e64 v151, v151, 0, vcc
	v_cndmask_b32_e64 v150, v150, 1.0, vcc
	v_cndmask_b32_e64 v160, v130, 1.0, vcc
	v_mov_b32_e32 v130, v20
	v_mov_b32_e32 v131, v12
	v_pk_mul_f32 v[130:131], v[130:131], v[150:151]
	v_cndmask_b32_e64 v153, v153, 0, vcc
	v_cndmask_b32_e64 v152, v152, 1.0, vcc
	v_cndmask_b32_e64 v154, v132, 1.0, vcc
	v_sub_f32_e32 v132, v130, v131
	v_mov_b32_e32 v130, v21
	v_mov_b32_e32 v131, v13
	v_pk_mul_f32 v[130:131], v[130:131], v[152:153]
	v_cndmask_b32_e64 v155, v133, 0, vcc
	v_sub_f32_e32 v130, v130, v131
	v_cvt_pk_bf16_f32 v130, v132, v130
	v_mov_b32_e32 v132, v22
	v_mov_b32_e32 v133, v14
	v_pk_mul_f32 v[132:133], v[132:133], v[160:161]
	v_pk_mul_f32 v[162:163], v[162:163], v[160:161]
	v_sub_f32_e32 v131, v132, v133
	v_mov_b32_e32 v132, v23
	v_mov_b32_e32 v133, v15
	v_pk_mul_f32 v[132:133], v[132:133], v[154:155]
	v_add_co_u32_e32 v148, vcc, s18, v148
	v_sub_f32_e32 v132, v132, v133
	v_cvt_pk_bf16_f32 v131, v131, v132
	v_mov_b32_e32 v132, v12
	v_mov_b32_e32 v133, v20
	v_pk_mul_f32 v[132:133], v[132:133], v[150:151]
	v_addc_co_u32_e32 v149, vcc, 0, v149, vcc
	v_add_f32_e32 v145, v133, v132
	v_mov_b32_e32 v132, v13
	v_mov_b32_e32 v133, v21
	v_pk_mul_f32 v[132:133], v[132:133], v[152:153]
	s_nop 0
	v_add_f32_e32 v132, v133, v132
	v_add_f32_e32 v133, v163, v162
	v_mov_b32_e32 v162, v15
	v_mov_b32_e32 v163, v23
	v_pk_mul_f32 v[162:163], v[162:163], v[154:155]
	v_cvt_pk_bf16_f32 v132, v145, v132
	s_nop 0
	v_add_f32_e32 v145, v163, v162
	v_cvt_pk_bf16_f32 v133, v133, v145
	global_store_dwordx4 v[148:149], v[130:133], off sc1
	s_nop 1
	v_mov_b32_e32 v130, v4
	v_mov_b32_e32 v131, v0
	v_pk_mul_f32 v[130:131], v[130:131], v[150:151]
	v_mov_b32_e32 v133, v2
	v_sub_f32_e32 v132, v130, v131
	v_mov_b32_e32 v130, v5
	v_mov_b32_e32 v131, v1
	v_pk_mul_f32 v[130:131], v[130:131], v[152:153]
	s_nop 0
	v_sub_f32_e32 v130, v130, v131
	v_cvt_pk_bf16_f32 v130, v132, v130
	v_mov_b32_e32 v132, v6
	v_pk_mul_f32 v[132:133], v[132:133], v[160:161]
	s_nop 0
	v_sub_f32_e32 v131, v132, v133
	v_mov_b32_e32 v132, v7
	v_mov_b32_e32 v133, v3
	v_pk_mul_f32 v[132:133], v[132:133], v[154:155]
	s_nop 0
	v_sub_f32_e32 v132, v132, v133
	v_cvt_pk_bf16_f32 v131, v131, v132
	v_mov_b32_e32 v132, v0
	v_mov_b32_e32 v133, v4
	v_pk_mul_f32 v[132:133], v[132:133], v[150:151]
	v_mov_b32_e32 v150, v2
	v_add_f32_e32 v145, v133, v132
	v_mov_b32_e32 v132, v1
	v_mov_b32_e32 v133, v5
	v_mov_b32_e32 v151, v6
	v_pk_mul_f32 v[132:133], v[132:133], v[152:153]
	v_pk_mul_f32 v[150:151], v[150:151], v[160:161]
	v_add_f32_e32 v132, v133, v132
	v_add_f32_e32 v133, v151, v150
	v_mov_b32_e32 v150, v3
	v_mov_b32_e32 v151, v7
	v_pk_mul_f32 v[150:151], v[150:151], v[154:155]
	v_cvt_pk_bf16_f32 v132, v145, v132
	s_nop 0
	v_add_f32_e32 v145, v151, v150
	v_cvt_pk_bf16_f32 v133, v133, v145
	global_store_dwordx4 v[148:149], v[130:133], off offset:256 sc1

; __device__ __forceinline__ unsigned cvt_pk_bf16(float lo, float hi) { unsigned r; asm volatile("v_cvt_pk_bf16_f32 %0, %1, %2" : "=v"(r) : "v"(lo), "v"(hi)); return r; }
;     template <int LDC> __device__ __forceinline__ void store_rope(const f32x4 (&acc)[2][2][4][2], bf16_t* base, int row0, int wc, int fq) const {
;         bf16_t* rp = base + (size_t)row0 * LDC; const int axis = wc >> 1, f0 = 16 * (wc & 1) + 4 * fq;
; #pragma unroll
;         for (int ai = 0; ai < 2; ++ai)
; #pragma unroll
;             for (int m = 0; m < 4; ++m) { const int row = row0 + ai * HALF + m * 16; bf16_t* rowp = rp + (size_t)(ai * HALF + m * 16) * LDC;
;                 const int t = row & (SEQ - 1), pos = axis ? (t & 63) : (t >> 6);
;                 f32x4 cs0 = *(const f32x4*)(TAB + (pos * 32 + f0) * 2), cs1 = *(const f32x4*)(TAB + (pos * 32 + f0) * 2 + 4);
;                 if (row >= ML) { cs0 = (f32x4){1.f, 0.f, 1.f, 0.f}; cs1 = cs0; }
; #pragma unroll
;                 for (int bj = 0; bj < 2; ++bj) { const f32x4 x1 = acc[ai][bj][m][0], x2 = acc[ai][bj][m][1];
;                     u32x4 w;
;                     w.x = cvt_pk_bf16(x1[0] * cs0[0] - x2[0] * cs0[1], x1[1] * cs0[2] - x2[1] * cs0[3]);
;                     w.y = cvt_pk_bf16(x1[2] * cs1[0] - x2[2] * cs1[1], x1[3] * cs1[2] - x2[3] * cs1[3]);
;                     w.z = cvt_pk_bf16(x2[0] * cs0[0] + x1[0] * cs0[1], x2[1] * cs0[2] + x1[1] * cs0[3]);
;                     w.w = cvt_pk_bf16(x2[2] * cs1[0] + x1[2] * cs1[1], x2[3] * cs1[2] + x1[3] * cs1[3]);
;                     *(u32x4*)(rowp + bj * HALF) = w; } }
.LBB0_598:
	s_and_b64 vcc, exec, s[18:19]
	s_cbranch_vccz .LBB0_600
	s_lshl_b32 s18, s63, 9
	s_add_u32 s18, s16, s18
	s_addc_u32 s19, s17, 0
	v_ashrrev_i32_e32 v147, 31, v146
	v_lshl_add_u64 v[130:131], v[146:147], 1, s[18:19]
	v_ashrrev_i32_e32 v145, 31, v144
	s_lshr_b32 s18, s45, 6
	v_lshlrev_b64 v[132:133], 11, v[144:145]
	v_mov_b32_e32 v147, s18
	v_lshl_add_u64 v[148:149], v[130:131], 0, v[132:133]
	v_cndmask_b32_e64 v130, v159, v147, s[40:41]
	v_lshlrev_b32_e32 v130, 5, v130
	v_lshl_add_u32 v145, v167, 2, s39
	v_and_b32_e32 v130, 0x7e0, v130
	v_add_lshl_u32 v130, v130, v145, 1
	v_ashrrev_i32_e32 v131, 31, v130
	v_lshlrev_b32_e32 v130, 2, v130
	v_add_u32_e32 v130, 0x20000, v130
	ds_read_b128 v[176:179], v130 offset:16
	ds_read_b128 v[130:133], v130
	s_movk_i32 s18, 0x3fff
	v_cmp_lt_i32_e32 vcc, s18, v144
	v_mov_b32_e32 v161, v108
	s_movk_i32 s18, 0x3fef
	s_addk_i32 s45, 0x80
	v_mov_b32_e32 v163, v56
	s_waitcnt lgkmcnt(0)
	v_cndmask_b32_e64 v153, v177, 0, vcc
	v_cndmask_b32_e64 v155, v131, 0, vcc
	v_cndmask_b32_e64 v154, v130, 1.0, vcc
	v_mov_b32_e32 v130, v126
	v_mov_b32_e32 v131, v122
	v_pk_mul_f32 v[130:131], v[130:131], v[154:155]
	v_cndmask_b32_e64 v133, v133, 0, vcc
	v_cndmask_b32_e64 v132, v132, 1.0, vcc
	v_sub_f32_e32 v160, v130, v131
	v_mov_b32_e32 v130, v127
	v_mov_b32_e32 v131, v123
	v_pk_mul_f32 v[130:131], v[130:131], v[132:133]
	v_cndmask_b32_e64 v152, v176, 1.0, vcc
	v_sub_f32_e32 v130, v130, v131
	v_cvt_pk_bf16_f32 v176, v160, v130
	v_mov_b32_e32 v130, v128
	v_mov_b32_e32 v131, v124
	v_pk_mul_f32 v[130:131], v[130:131], v[152:153]
	v_cndmask_b32_e64 v151, v179, 0, vcc
	v_cndmask_b32_e64 v150, v178, 1.0, vcc
	v_sub_f32_e32 v160, v130, v131
	v_mov_b32_e32 v130, v129
	v_mov_b32_e32 v131, v125
	v_pk_mul_f32 v[130:131], v[130:131], v[150:151]
	v_cmp_lt_i32_e32 vcc, s18, v144
	v_sub_f32_e32 v130, v130, v131
	v_cvt_pk_bf16_f32 v177, v160, v130
	v_mov_b32_e32 v130, v122
	v_mov_b32_e32 v131, v126
	v_pk_mul_f32 v[130:131], v[130:131], v[154:155]
	s_movk_i32 s18, 0x7000
	v_add_f32_e32 v160, v131, v130
	v_mov_b32_e32 v130, v123
	v_mov_b32_e32 v131, v127
	v_pk_mul_f32 v[130:131], v[130:131], v[132:133]
	s_nop 0
	v_add_f32_e32 v130, v131, v130
	v_cvt_pk_bf16_f32 v178, v160, v130
	v_mov_b32_e32 v130, v124
	v_mov_b32_e32 v131, v128
	v_pk_mul_f32 v[130:131], v[130:131], v[152:153]
	s_nop 0
	v_add_f32_e32 v160, v131, v130
	v_mov_b32_e32 v130, v125
	v_mov_b32_e32 v131, v129
	v_pk_mul_f32 v[130:131], v[130:131], v[150:151]
	s_nop 0
	v_add_f32_e32 v130, v131, v130
	v_cvt_pk_bf16_f32 v179, v160, v130
	v_mov_b32_e32 v130, v114
	v_mov_b32_e32 v131, v106
	v_pk_mul_f32 v[130:131], v[130:131], v[154:155]
	global_store_dwordx4 v[148:149], v[176:179], off offset:-4096 sc1
	v_sub_f32_e32 v160, v130, v131
	v_mov_b32_e32 v130, v115
	v_mov_b32_e32 v131, v107
	v_pk_mul_f32 v[130:131], v[130:131], v[132:133]
	s_nop 0
	v_sub_f32_e32 v130, v130, v131
	v_cvt_pk_bf16_f32 v130, v160, v130
	v_mov_b32_e32 v160, v116
	v_pk_mul_f32 v[160:161], v[160:161], v[152:153]
	s_nop 0
	v_sub_f32_e32 v131, v160, v161
	v_mov_b32_e32 v160, v117
	v_mov_b32_e32 v161, v109
	v_pk_mul_f32 v[160:161], v[160:161], v[150:151]
	s_nop 0
	v_sub_f32_e32 v160, v160, v161
	v_cvt_pk_bf16_f32 v131, v131, v160
	v_mov_b32_e32 v160, v106
	v_mov_b32_e32 v161, v114
	v_pk_mul_f32 v[154:155], v[160:161], v[154:155]
	v_mov_b32_e32 v161, v90
	v_add_f32_e32 v160, v155, v154
	v_mov_b32_e32 v154, v107
	v_mov_b32_e32 v155, v115
	v_pk_mul_f32 v[132:133], v[154:155], v[132:133]
	v_mov_b32_e32 v154, v108
	v_mov_b32_e32 v155, v116
	v_pk_mul_f32 v[152:153], v[154:155], v[152:153]
	v_add_f32_e32 v132, v133, v132
	v_add_f32_e32 v133, v153, v152
	v_mov_b32_e32 v152, v109
	v_mov_b32_e32 v153, v117
	v_pk_mul_f32 v[150:151], v[152:153], v[150:151]
	v_cvt_pk_bf16_f32 v132, v160, v132
	v_mov_b32_e32 v154, v118
	v_add_f32_e32 v150, v151, v150
	v_cvt_pk_bf16_f32 v133, v133, v150
	global_store_dwordx4 v[148:149], v[130:133], off offset:-3840 sc1
	v_mov_b32_e32 v155, v110
	s_nop 0
	v_or_b32_e32 v130, 16, v144
	v_cndmask_b32_e64 v130, v130, v147, s[40:41]
	v_lshlrev_b32_e32 v130, 5, v130
	v_and_b32_e32 v130, 0x7e0, v130
	v_add_lshl_u32 v130, v130, v145, 1
	v_ashrrev_i32_e32 v131, 31, v130
	v_lshlrev_b32_e32 v130, 2, v130
	v_add_u32_e32 v130, 0x20000, v130
	ds_read_b128 v[176:179], v130 offset:16
	ds_read_b128 v[130:133], v130
	s_waitcnt lgkmcnt(1)
	v_cndmask_b32_e64 v151, v177, 0, vcc
	s_waitcnt lgkmcnt(0)
; __device__ __forceinline__ unsigned cvt_pk_bf16(float lo, float hi) { unsigned r; asm volatile("v_cvt_pk_bf16_f32 %0, %1, %2" : "=v"(r) : "v"(lo), "v"(hi)); return r; }
;     template <int LDC> __device__ __forceinline__ void store_rope(const f32x4 (&acc)[2][2][4][2], bf16_t* base, int row0, int wc, int fq) const {
;         bf16_t* rp = base + (size_t)row0 * LDC; const int axis = wc >> 1, f0 = 16 * (wc & 1) + 4 * fq;
; #pragma unroll
;         for (int ai = 0; ai < 2; ++ai)
; #pragma unroll
;             for (int m = 0; m < 4; ++m) { const int row = row0 + ai * HALF + m * 16; bf16_t* rowp = rp + (size_t)(ai * HALF + m * 16) * LDC;
;                 const int t = row & (SEQ - 1), pos = axis ? (t & 63) : (t >> 6);
;                 f32x4 cs0 = *(const f32x4*)(TAB + (pos * 32 + f0) * 2), cs1 = *(const f32x4*)(TAB + (pos * 32 + f0) * 2 + 4);
;                 if (row >= ML) { cs0 = (f32x4){1.f, 0.f, 1.f, 0.f}; cs1 = cs0; }
; #pragma unroll
;                 for (int bj = 0; bj < 2; ++bj) { const f32x4 x1 = acc[ai][bj][m][0], x2 = acc[ai][bj][m][1];
;                     u32x4 w;
;                     w.x = cvt_pk_bf16(x1[0] * cs0[0] - x2[0] * cs0[1], x1[1] * cs0[2] - x2[1] * cs0[3]);
;                     w.y = cvt_pk_bf16(x1[2] * cs1[0] - x2[2] * cs1[1], x1[3] * cs1[2] - x2[3] * cs1[3]);
;                     w.z = cvt_pk_bf16(x2[0] * cs0[0] + x1[0] * cs0[1], x2[1] * cs0[2] + x1[1] * cs0[3]);
;                     w.w = cvt_pk_bf16(x2[2] * cs1[0] + x1[2] * cs1[1], x2[3] * cs1[2] + x1[3] * cs1[3]);
;                     *(u32x4*)(rowp + bj * HALF) = w; } }
	v_cndmask_b32_e64 v153, v131, 0, vcc
	v_cndmask_b32_e64 v152, v130, 1.0, vcc
	v_pk_mul_f32 v[154:155], v[154:155], v[152:153]
	v_cndmask_b32_e64 v133, v133, 0, vcc
	v_cndmask_b32_e64 v132, v132, 1.0, vcc
	v_sub_f32_e32 v160, v154, v155
	v_mov_b32_e32 v154, v119
	v_mov_b32_e32 v155, v111
	v_pk_mul_f32 v[154:155], v[154:155], v[132:133]
	v_cndmask_b32_e64 v150, v176, 1.0, vcc
	v_sub_f32_e32 v154, v154, v155
	v_cvt_pk_bf16_f32 v176, v160, v154
	v_mov_b32_e32 v154, v120
	v_mov_b32_e32 v155, v112
	v_pk_mul_f32 v[154:155], v[154:155], v[150:151]
	v_cndmask_b32_e64 v131, v179, 0, vcc
	v_cndmask_b32_e64 v130, v178, 1.0, vcc
	v_sub_f32_e32 v160, v154, v155
	v_mov_b32_e32 v154, v121
	v_mov_b32_e32 v155, v113
	v_pk_mul_f32 v[154:155], v[154:155], v[130:131]
	s_nop 0
	v_sub_f32_e32 v154, v154, v155
	v_cvt_pk_bf16_f32 v177, v160, v154
	v_mov_b32_e32 v154, v110
	v_mov_b32_e32 v155, v118
	v_pk_mul_f32 v[154:155], v[154:155], v[152:153]
	s_nop 0
	v_add_f32_e32 v160, v155, v154
	v_mov_b32_e32 v154, v111
	v_mov_b32_e32 v155, v119
	v_pk_mul_f32 v[154:155], v[154:155], v[132:133]
	s_nop 0
	v_add_f32_e32 v154, v155, v154
	v_cvt_pk_bf16_f32 v178, v160, v154
	v_mov_b32_e32 v154, v112
	v_mov_b32_e32 v155, v120
	v_pk_mul_f32 v[154:155], v[154:155], v[150:151]
	s_nop 0
	v_add_f32_e32 v160, v155, v154
	v_mov_b32_e32 v154, v113
	v_mov_b32_e32 v155, v121
	v_pk_mul_f32 v[154:155], v[154:155], v[130:131]
	s_nop 0
	v_add_f32_e32 v154, v155, v154
	v_cvt_pk_bf16_f32 v179, v160, v154
	v_mov_b32_e32 v160, v98
	v_pk_mul_f32 v[160:161], v[160:161], v[152:153]
	v_add_co_u32_e32 v154, vcc, s18, v148
	v_sub_f32_e32 v162, v160, v161
	v_mov_b32_e32 v160, v99
	v_mov_b32_e32 v161, v91
	v_pk_mul_f32 v[160:161], v[160:161], v[132:133]
	v_addc_co_u32_e32 v155, vcc, 0, v149, vcc
	v_sub_f32_e32 v160, v160, v161
	global_store_dwordx4 v[154:155], v[176:179], off sc1
	v_mov_b32_e32 v161, v92
	s_movk_i32 s18, 0x3fdf
	v_cvt_pk_bf16_f32 v176, v162, v160
	v_mov_b32_e32 v160, v100
	v_pk_mul_f32 v[160:161], v[160:161], v[150:151]
	v_cmp_lt_i32_e32 vcc, s18, v144
	v_sub_f32_e32 v162, v160, v161
	v_mov_b32_e32 v160, v101
	v_mov_b32_e32 v161, v93
	v_pk_mul_f32 v[160:161], v[160:161], v[130:131]
	s_mov_b32 s18, 0xf000
	v_sub_f32_e32 v160, v160, v161
	v_cvt_pk_bf16_f32 v177, v162, v160
	v_mov_b32_e32 v160, v90
	v_mov_b32_e32 v161, v98
	v_pk_mul_f32 v[152:153], v[160:161], v[152:153]
	v_mov_b32_e32 v161, v74
	v_add_f32_e32 v160, v153, v152
	v_mov_b32_e32 v152, v91
	v_mov_b32_e32 v153, v99
	v_pk_mul_f32 v[132:133], v[152:153], v[132:133]
	s_nop 0
	v_add_f32_e32 v132, v133, v132
	v_cvt_pk_bf16_f32 v178, v160, v132
	v_mov_b32_e32 v132, v92
	v_mov_b32_e32 v133, v100
	v_pk_mul_f32 v[132:133], v[132:133], v[150:151]
	s_nop 0
	v_add_f32_e32 v150, v133, v132
	v_mov_b32_e32 v132, v93
	v_mov_b32_e32 v133, v101
	v_pk_mul_f32 v[130:131], v[132:133], v[130:131]
	s_nop 0
	v_add_f32_e32 v130, v131, v130
	v_cvt_pk_bf16_f32 v179, v150, v130
	v_or_b32_e32 v130, 32, v144
	v_cndmask_b32_e64 v130, v130, v147, s[40:41]
	v_lshlrev_b32_e32 v130, 5, v130
	v_and_b32_e32 v130, 0x7e0, v130
	v_add_lshl_u32 v130, v130, v145, 1
	v_ashrrev_i32_e32 v131, 31, v130
	global_store_dwordx4 v[154:155], v[176:179], off offset:256 sc1
	v_lshlrev_b32_e32 v130, 2, v130
	v_add_u32_e32 v130, 0x20000, v130
	ds_read_b128 v[176:179], v130 offset:16
	ds_read_b128 v[130:133], v130
	v_mov_b32_e32 v154, v102
	v_mov_b32_e32 v155, v94
	s_waitcnt lgkmcnt(1)
	v_cndmask_b32_e64 v151, v177, 0, vcc
	s_waitcnt lgkmcnt(0)
	v_cndmask_b32_e64 v153, v131, 0, vcc
	v_cndmask_b32_e64 v152, v130, 1.0, vcc
	v_pk_mul_f32 v[154:155], v[154:155], v[152:153]
	v_cndmask_b32_e64 v133, v133, 0, vcc
	v_cndmask_b32_e64 v132, v132, 1.0, vcc
	v_sub_f32_e32 v160, v154, v155
	v_mov_b32_e32 v154, v103
	v_mov_b32_e32 v155, v95
	v_pk_mul_f32 v[154:155], v[154:155], v[132:133]
	v_cndmask_b32_e64 v150, v176, 1.0, vcc
	v_sub_f32_e32 v154, v154, v155
	v_cvt_pk_bf16_f32 v176, v160, v154
	v_mov_b32_e32 v154, v104
	v_mov_b32_e32 v155, v96
	v_pk_mul_f32 v[154:155], v[154:155], v[150:151]
	v_cndmask_b32_e64 v131, v179, 0, vcc
	v_cndmask_b32_e64 v130, v178, 1.0, vcc
	v_sub_f32_e32 v160, v154, v155
	v_mov_b32_e32 v154, v105
	v_mov_b32_e32 v155, v97
	v_pk_mul_f32 v[154:155], v[154:155], v[130:131]
	s_nop 0
	v_sub_f32_e32 v154, v154, v155
	v_cvt_pk_bf16_f32 v177, v160, v154
	v_mov_b32_e32 v154, v94
	v_mov_b32_e32 v155, v102
	v_pk_mul_f32 v[154:155], v[154:155], v[152:153]
	s_nop 0
	v_add_f32_e32 v160, v155, v154
	v_mov_b32_e32 v154, v95
	v_mov_b32_e32 v155, v103
	v_pk_mul_f32 v[154:155], v[154:155], v[132:133]
	s_nop 0
	v_add_f32_e32 v154, v155, v154
	v_cvt_pk_bf16_f32 v178, v160, v154
	v_mov_b32_e32 v154, v96
	v_mov_b32_e32 v155, v104
	v_pk_mul_f32 v[154:155], v[154:155], v[150:151]
	s_nop 0
	v_add_f32_e32 v160, v155, v154
	v_mov_b32_e32 v154, v97
	v_mov_b32_e32 v155, v105
	v_pk_mul_f32 v[154:155], v[154:155], v[130:131]
	s_nop 0
	v_add_f32_e32 v154, v155, v154
	v_cvt_pk_bf16_f32 v179, v160, v154
	v_mov_b32_e32 v160, v82
	v_pk_mul_f32 v[160:161], v[160:161], v[152:153]
	v_add_co_u32_e32 v154, vcc, s18, v148
	v_sub_f32_e32 v162, v160, v161
	v_mov_b32_e32 v160, v83
	v_mov_b32_e32 v161, v75
	v_pk_mul_f32 v[160:161], v[160:161], v[132:133]
	v_addc_co_u32_e32 v155, vcc, 0, v149, vcc
	v_sub_f32_e32 v160, v160, v161
	global_store_dwordx4 v[154:155], v[176:179], off sc1
	v_mov_b32_e32 v161, v76
	s_movk_i32 s18, 0x3fcf
	v_cvt_pk_bf16_f32 v176, v162, v160
	v_mov_b32_e32 v160, v84
	v_pk_mul_f32 v[160:161], v[160:161], v[150:151]
	v_cmp_lt_i32_e32 vcc, s18, v144
	v_sub_f32_e32 v162, v160, v161
	v_mov_b32_e32 v160, v85
	v_mov_b32_e32 v161, v77
	v_pk_mul_f32 v[160:161], v[160:161], v[130:131]
	s_mov_b32 s18, 0x17000
	v_sub_f32_e32 v160, v160, v161
	v_cvt_pk_bf16_f32 v177, v162, v160
	v_mov_b32_e32 v160, v74
	v_mov_b32_e32 v161, v82
	v_pk_mul_f32 v[152:153], v[160:161], v[152:153]
	v_mov_b32_e32 v161, v66
	v_add_f32_e32 v160, v153, v152
	v_mov_b32_e32 v152, v75
	v_mov_b32_e32 v153, v83
	v_pk_mul_f32 v[132:133], v[152:153], v[132:133]
	v_mov_b32_e32 v162, v48
	v_add_f32_e32 v132, v133, v132
	v_cvt_pk_bf16_f32 v178, v160, v132
	v_mov_b32_e32 v132, v76
	v_mov_b32_e32 v133, v84
	v_pk_mul_f32 v[132:133], v[132:133], v[150:151]
	v_mov_b32_e32 v160, v70
	v_add_f32_e32 v150, v133, v132
	v_mov_b32_e32 v132, v77
	v_mov_b32_e32 v133, v85
	v_pk_mul_f32 v[130:131], v[132:133], v[130:131]
	s_nop 0
	v_add_f32_e32 v130, v131, v130
	v_cvt_pk_bf16_f32 v179, v150, v130
	v_or_b32_e32 v130, 48, v144
	v_cndmask_b32_e64 v130, v130, v147, s[40:41]
	v_lshlrev_b32_e32 v130, 5, v130
	v_and_b32_e32 v130, 0x7e0, v130
	v_add_lshl_u32 v130, v130, v145, 1
	v_ashrrev_i32_e32 v131, 31, v130
	global_store_dwordx4 v[154:155], v[176:179], off offset:256 sc1
	v_lshlrev_b32_e32 v130, 2, v130
	v_add_u32_e32 v130, 0x20000, v130
	ds_read_b128 v[176:179], v130 offset:16
	ds_read_b128 v[130:133], v130
	v_mov_b32_e32 v154, v86
	v_mov_b32_e32 v155, v78
	s_waitcnt lgkmcnt(1)
; __device__ __forceinline__ unsigned cvt_pk_bf16(float lo, float hi) { unsigned r; asm volatile("v_cvt_pk_bf16_f32 %0, %1, %2" : "=v"(r) : "v"(lo), "v"(hi)); return r; }
;     template <int LDC> __device__ __forceinline__ void store_rope(const f32x4 (&acc)[2][2][4][2], bf16_t* base, int row0, int wc, int fq) const {
;         bf16_t* rp = base + (size_t)row0 * LDC; const int axis = wc >> 1, f0 = 16 * (wc & 1) + 4 * fq;
; #pragma unroll
;         for (int ai = 0; ai < 2; ++ai)
; #pragma unroll
;             for (int m = 0; m < 4; ++m) { const int row = row0 + ai * HALF + m * 16; bf16_t* rowp = rp + (size_t)(ai * HALF + m * 16) * LDC;
;                 const int t = row & (SEQ - 1), pos = axis ? (t & 63) : (t >> 6);
;                 f32x4 cs0 = *(const f32x4*)(TAB + (pos * 32 + f0) * 2), cs1 = *(const f32x4*)(TAB + (pos * 32 + f0) * 2 + 4);
;                 if (row >= ML) { cs0 = (f32x4){1.f, 0.f, 1.f, 0.f}; cs1 = cs0; }
; #pragma unroll
;                 for (int bj = 0; bj < 2; ++bj) { const f32x4 x1 = acc[ai][bj][m][0], x2 = acc[ai][bj][m][1];
;                     u32x4 w;
;                     w.x = cvt_pk_bf16(x1[0] * cs0[0] - x2[0] * cs0[1], x1[1] * cs0[2] - x2[1] * cs0[3]);
;                     w.y = cvt_pk_bf16(x1[2] * cs1[0] - x2[2] * cs1[1], x1[3] * cs1[2] - x2[3] * cs1[3]);
;                     w.z = cvt_pk_bf16(x2[0] * cs0[0] + x1[0] * cs0[1], x2[1] * cs0[2] + x1[1] * cs0[3]);
;                     w.w = cvt_pk_bf16(x2[2] * cs1[0] + x1[2] * cs1[1], x2[3] * cs1[2] + x1[3] * cs1[3]);
;                     *(u32x4*)(rowp + bj * HALF) = w; } }
	v_cndmask_b32_e64 v151, v177, 0, vcc
	s_waitcnt lgkmcnt(0)
	v_cndmask_b32_e64 v153, v131, 0, vcc
	v_cndmask_b32_e64 v152, v130, 1.0, vcc
	v_pk_mul_f32 v[154:155], v[154:155], v[152:153]
	v_cndmask_b32_e64 v133, v133, 0, vcc
	v_cndmask_b32_e64 v132, v132, 1.0, vcc
	v_sub_f32_e32 v147, v154, v155
	v_mov_b32_e32 v154, v87
	v_mov_b32_e32 v155, v79
	v_pk_mul_f32 v[154:155], v[154:155], v[132:133]
	v_cndmask_b32_e64 v150, v176, 1.0, vcc
	v_sub_f32_e32 v154, v154, v155
	v_cvt_pk_bf16_f32 v176, v147, v154
	v_mov_b32_e32 v154, v88
	v_mov_b32_e32 v155, v80
	v_pk_mul_f32 v[154:155], v[154:155], v[150:151]
	v_cndmask_b32_e64 v131, v179, 0, vcc
	v_cndmask_b32_e64 v130, v178, 1.0, vcc
	v_sub_f32_e32 v147, v154, v155
	v_mov_b32_e32 v154, v89
	v_mov_b32_e32 v155, v81
	v_pk_mul_f32 v[154:155], v[154:155], v[130:131]
	v_pk_mul_f32 v[160:161], v[160:161], v[152:153]
	v_sub_f32_e32 v154, v154, v155
	v_cvt_pk_bf16_f32 v177, v147, v154
	v_mov_b32_e32 v154, v78
	v_mov_b32_e32 v155, v86
	v_pk_mul_f32 v[154:155], v[154:155], v[152:153]
	s_nop 0
	v_add_f32_e32 v147, v155, v154
	v_mov_b32_e32 v154, v79
	v_mov_b32_e32 v155, v87
	v_pk_mul_f32 v[154:155], v[154:155], v[132:133]
	s_nop 0
	v_add_f32_e32 v154, v155, v154
	v_cvt_pk_bf16_f32 v178, v147, v154
	v_mov_b32_e32 v154, v80
	v_mov_b32_e32 v155, v88
	v_pk_mul_f32 v[154:155], v[154:155], v[150:151]
	s_nop 0
	v_add_f32_e32 v147, v155, v154
	v_mov_b32_e32 v154, v81
	v_mov_b32_e32 v155, v89
	v_pk_mul_f32 v[154:155], v[154:155], v[130:131]
	s_nop 0
	v_add_f32_e32 v154, v155, v154
	v_cvt_pk_bf16_f32 v179, v147, v154
	v_sub_f32_e32 v147, v160, v161
	v_mov_b32_e32 v160, v71
	v_mov_b32_e32 v161, v67
	v_add_co_u32_e32 v154, vcc, s18, v148
	v_pk_mul_f32 v[160:161], v[160:161], v[132:133]
	s_nop 0
	v_addc_co_u32_e32 v155, vcc, 0, v149, vcc
	v_sub_f32_e32 v160, v160, v161
	global_store_dwordx4 v[154:155], v[176:179], off sc1
	v_mov_b32_e32 v161, v68
	s_lshr_b32 s18, s45, 6
	v_cvt_pk_bf16_f32 v176, v147, v160
	v_mov_b32_e32 v160, v72
	v_pk_mul_f32 v[160:161], v[160:161], v[150:151]
	s_nop 0
	v_sub_f32_e32 v147, v160, v161
	v_mov_b32_e32 v160, v73
	v_mov_b32_e32 v161, v69
	v_pk_mul_f32 v[160:161], v[160:161], v[130:131]
	s_nop 0
	v_sub_f32_e32 v160, v160, v161
	v_cvt_pk_bf16_f32 v177, v147, v160
	v_mov_b32_e32 v160, v66
	v_mov_b32_e32 v161, v70
	v_pk_mul_f32 v[152:153], v[160:161], v[152:153]
	v_mov_b32_e32 v160, v50
	v_add_f32_e32 v147, v153, v152
	v_mov_b32_e32 v152, v67
	v_mov_b32_e32 v153, v71
	v_pk_mul_f32 v[132:133], v[152:153], v[132:133]
	v_mov_b32_e32 v161, v42
	v_add_f32_e32 v132, v133, v132
	v_cvt_pk_bf16_f32 v178, v147, v132
	v_mov_b32_e32 v132, v68
	v_mov_b32_e32 v133, v72
	v_pk_mul_f32 v[132:133], v[132:133], v[150:151]
	s_nop 0
	v_add_f32_e32 v147, v133, v132
	v_mov_b32_e32 v132, v69
	v_mov_b32_e32 v133, v73
	v_pk_mul_f32 v[130:131], v[132:133], v[130:131]
	s_nop 0
	v_add_f32_e32 v130, v131, v130
	v_cvt_pk_bf16_f32 v179, v147, v130
	v_mov_b32_e32 v130, s18
	v_cndmask_b32_e64 v130, v159, v130, s[40:41]
	v_lshlrev_b32_e32 v130, 5, v130
	v_and_b32_e32 v130, 0x7e0, v130
	v_add_lshl_u32 v130, v130, v145, 1
	v_ashrrev_i32_e32 v131, 31, v130
	global_store_dwordx4 v[154:155], v[176:179], off offset:256 sc1
	v_lshlrev_b32_e32 v130, 2, v130
	v_add_u32_e32 v130, 0x20000, v130
	ds_read_b128 v[176:179], v130 offset:16
	ds_read_b128 v[130:133], v130
	s_movk_i32 s18, 0x3f7f
	v_cmp_lt_i32_e32 vcc, s18, v144
	v_mov_b32_e32 v154, v62
	v_mov_b32_e32 v155, v58
	s_mov_b32 s18, 0x3f000
	s_waitcnt lgkmcnt(1)
	v_cndmask_b32_e64 v151, v177, 0, vcc
	s_waitcnt lgkmcnt(0)
	v_cndmask_b32_e64 v153, v131, 0, vcc
	v_cndmask_b32_e64 v152, v130, 1.0, vcc
	v_pk_mul_f32 v[154:155], v[154:155], v[152:153]
	v_cndmask_b32_e64 v133, v133, 0, vcc
	v_cndmask_b32_e64 v132, v132, 1.0, vcc
	v_sub_f32_e32 v147, v154, v155
	v_mov_b32_e32 v154, v63
	v_mov_b32_e32 v155, v59
	v_pk_mul_f32 v[154:155], v[154:155], v[132:133]
	v_cndmask_b32_e64 v150, v176, 1.0, vcc
	v_sub_f32_e32 v154, v154, v155
	v_cvt_pk_bf16_f32 v176, v147, v154
	v_mov_b32_e32 v154, v64
	v_mov_b32_e32 v155, v60
	v_pk_mul_f32 v[154:155], v[154:155], v[150:151]
	v_cndmask_b32_e64 v131, v179, 0, vcc
	v_cndmask_b32_e64 v130, v178, 1.0, vcc
	v_sub_f32_e32 v147, v154, v155
	v_mov_b32_e32 v154, v65
	v_mov_b32_e32 v155, v61
	v_pk_mul_f32 v[154:155], v[154:155], v[130:131]
	v_pk_mul_f32 v[160:161], v[160:161], v[152:153]
	v_sub_f32_e32 v154, v154, v155
	v_cvt_pk_bf16_f32 v177, v147, v154
	v_mov_b32_e32 v154, v58
	v_mov_b32_e32 v155, v62
	v_pk_mul_f32 v[154:155], v[154:155], v[152:153]
	s_nop 0
	v_add_f32_e32 v147, v155, v154
	v_mov_b32_e32 v154, v59
	v_mov_b32_e32 v155, v63
	v_pk_mul_f32 v[154:155], v[154:155], v[132:133]
	s_nop 0
	v_add_f32_e32 v154, v155, v154
	v_cvt_pk_bf16_f32 v178, v147, v154
	v_mov_b32_e32 v154, v60
	v_mov_b32_e32 v155, v64
	v_pk_mul_f32 v[154:155], v[154:155], v[150:151]
	s_nop 0
	v_add_f32_e32 v147, v155, v154
	v_mov_b32_e32 v154, v61
	v_mov_b32_e32 v155, v65
	v_pk_mul_f32 v[154:155], v[154:155], v[130:131]
	s_nop 0
	v_add_f32_e32 v154, v155, v154
	v_cvt_pk_bf16_f32 v179, v147, v154
	v_sub_f32_e32 v147, v160, v161
	v_mov_b32_e32 v160, v51
	v_mov_b32_e32 v161, v43
	v_pk_mul_f32 v[160:161], v[160:161], v[132:133]
	v_add_co_u32_e32 v154, vcc, s18, v148
	v_sub_f32_e32 v159, v160, v161
	v_mov_b32_e32 v160, v52
	v_mov_b32_e32 v161, v44
	v_addc_co_u32_e32 v155, vcc, 0, v149, vcc
	v_pk_mul_f32 v[160:161], v[160:161], v[150:151]
	global_store_dwordx4 v[154:155], v[176:179], off sc1
	s_movk_i32 s18, 0x3f6f
	v_cmp_lt_i32_e32 vcc, s18, v144
	v_cvt_pk_bf16_f32 v176, v147, v159
	v_sub_f32_e32 v147, v160, v161
	v_mov_b32_e32 v160, v53
	v_mov_b32_e32 v161, v45
	v_pk_mul_f32 v[160:161], v[160:161], v[130:131]
	s_mov_b32 s18, 0x47000
	v_sub_f32_e32 v159, v160, v161
	v_mov_b32_e32 v160, v42
	v_mov_b32_e32 v161, v50
	v_pk_mul_f32 v[152:153], v[160:161], v[152:153]
	v_cvt_pk_bf16_f32 v177, v147, v159
	s_nop 0
	v_add_f32_e32 v147, v153, v152
	v_mov_b32_e32 v152, v43
	v_mov_b32_e32 v153, v51
	v_pk_mul_f32 v[132:133], v[152:153], v[132:133]
	s_nop 0
	v_add_f32_e32 v132, v133, v132
	v_cvt_pk_bf16_f32 v178, v147, v132
	v_mov_b32_e32 v132, v44
	v_mov_b32_e32 v133, v52
	v_pk_mul_f32 v[132:133], v[132:133], v[150:151]
	s_nop 0
	v_add_f32_e32 v147, v133, v132
	v_mov_b32_e32 v132, v45
	v_mov_b32_e32 v133, v53
	v_pk_mul_f32 v[130:131], v[132:133], v[130:131]
	s_nop 0
	v_add_f32_e32 v130, v131, v130
	v_cvt_pk_bf16_f32 v179, v147, v130
	v_add_u32_e32 v130, 0x90, v144
	v_lshrrev_b32_e32 v131, 6, v130
	v_cndmask_b32_e64 v130, v130, v131, s[40:41]
	v_lshlrev_b32_e32 v130, 5, v130
	v_and_b32_e32 v130, 0x7e0, v130
	v_add_lshl_u32 v130, v130, v145, 1
	v_ashrrev_i32_e32 v131, 31, v130
	global_store_dwordx4 v[154:155], v[176:179], off offset:256 sc1
	v_lshlrev_b32_e32 v150, 2, v130
	v_add_u32_e32 v150, 0x20000, v150
	ds_read_b128 v[130:133], v150 offset:16
	ds_read_b128 v[150:153], v150
	s_waitcnt lgkmcnt(1)
; __device__ __forceinline__ unsigned cvt_pk_bf16(float lo, float hi) { unsigned r; asm volatile("v_cvt_pk_bf16_f32 %0, %1, %2" : "=v"(r) : "v"(lo), "v"(hi)); return r; }
;     template <int LDC> __device__ __forceinline__ void store_rope(const f32x4 (&acc)[2][2][4][2], bf16_t* base, int row0, int wc, int fq) const {
;         bf16_t* rp = base + (size_t)row0 * LDC; const int axis = wc >> 1, f0 = 16 * (wc & 1) + 4 * fq;
; #pragma unroll
;         for (int ai = 0; ai < 2; ++ai)
; #pragma unroll
;             for (int m = 0; m < 4; ++m) { const int row = row0 + ai * HALF + m * 16; bf16_t* rowp = rp + (size_t)(ai * HALF + m * 16) * LDC;
;                 const int t = row & (SEQ - 1), pos = axis ? (t & 63) : (t >> 6);
;                 f32x4 cs0 = *(const f32x4*)(TAB + (pos * 32 + f0) * 2), cs1 = *(const f32x4*)(TAB + (pos * 32 + f0) * 2 + 4);
;                 if (row >= ML) { cs0 = (f32x4){1.f, 0.f, 1.f, 0.f}; cs1 = cs0; }
; #pragma unroll
;                 for (int bj = 0; bj < 2; ++bj) { const f32x4 x1 = acc[ai][bj][m][0], x2 = acc[ai][bj][m][1];
;                     u32x4 w;
;                     w.x = cvt_pk_bf16(x1[0] * cs0[0] - x2[0] * cs0[1], x1[1] * cs0[2] - x2[1] * cs0[3]);
;                     w.y = cvt_pk_bf16(x1[2] * cs1[0] - x2[2] * cs1[1], x1[3] * cs1[2] - x2[3] * cs1[3]);
;                     w.z = cvt_pk_bf16(x2[0] * cs0[0] + x1[0] * cs0[1], x2[1] * cs0[2] + x1[1] * cs0[3]);
;                     w.w = cvt_pk_bf16(x2[2] * cs1[0] + x1[2] * cs1[1], x2[3] * cs1[2] + x1[3] * cs1[3]);
;                     *(u32x4*)(rowp + bj * HALF) = w; } }
	v_cndmask_b32_e64 v161, v131, 0, vcc
	s_waitcnt lgkmcnt(0)
	v_cndmask_b32_e64 v151, v151, 0, vcc
	v_cndmask_b32_e64 v150, v150, 1.0, vcc
	v_cndmask_b32_e64 v160, v130, 1.0, vcc
	v_mov_b32_e32 v130, v54
	v_mov_b32_e32 v131, v46
	v_pk_mul_f32 v[130:131], v[130:131], v[150:151]
	v_cndmask_b32_e64 v153, v153, 0, vcc
	v_cndmask_b32_e64 v152, v152, 1.0, vcc
	v_cndmask_b32_e64 v154, v132, 1.0, vcc
	v_sub_f32_e32 v132, v130, v131
	v_mov_b32_e32 v130, v55
	v_mov_b32_e32 v131, v47
	v_pk_mul_f32 v[130:131], v[130:131], v[152:153]
	v_cndmask_b32_e64 v155, v133, 0, vcc
	v_sub_f32_e32 v130, v130, v131
	v_cvt_pk_bf16_f32 v130, v132, v130
	v_mov_b32_e32 v132, v56
	v_mov_b32_e32 v133, v48
	v_pk_mul_f32 v[132:133], v[132:133], v[160:161]
	v_pk_mul_f32 v[162:163], v[162:163], v[160:161]
	v_sub_f32_e32 v131, v132, v133
	v_mov_b32_e32 v132, v57
	v_mov_b32_e32 v133, v49
	v_pk_mul_f32 v[132:133], v[132:133], v[154:155]
	s_nop 0
	v_sub_f32_e32 v132, v132, v133
	v_cvt_pk_bf16_f32 v131, v131, v132
	v_mov_b32_e32 v132, v46
	v_mov_b32_e32 v133, v54
	v_pk_mul_f32 v[132:133], v[132:133], v[150:151]
	s_nop 0
	v_add_f32_e32 v147, v133, v132
	v_mov_b32_e32 v132, v47
	v_mov_b32_e32 v133, v55
	v_pk_mul_f32 v[132:133], v[132:133], v[152:153]
	s_nop 0
	v_add_f32_e32 v132, v133, v132
	v_add_f32_e32 v133, v163, v162
	v_mov_b32_e32 v162, v49
	v_mov_b32_e32 v163, v57
	v_pk_mul_f32 v[162:163], v[162:163], v[154:155]
	v_cvt_pk_bf16_f32 v132, v147, v132
	s_nop 0
	v_add_f32_e32 v147, v163, v162
	v_add_co_u32_e32 v162, vcc, s18, v148
	v_cvt_pk_bf16_f32 v133, v133, v147
	s_movk_i32 s18, 0x3f5f
	s_nop 0
	v_addc_co_u32_e32 v163, vcc, 0, v149, vcc
	global_store_dwordx4 v[162:163], v[130:133], off sc1
	v_cmp_lt_i32_e32 vcc, s18, v144
	s_mov_b32 s18, 0x4f000
	v_mov_b32_e32 v130, v34
	v_mov_b32_e32 v131, v24
	v_pk_mul_f32 v[130:131], v[130:131], v[150:151]
	v_mov_b32_e32 v133, v26
	v_sub_f32_e32 v132, v130, v131
	v_mov_b32_e32 v130, v35
	v_mov_b32_e32 v131, v25
	v_pk_mul_f32 v[130:131], v[130:131], v[152:153]
	s_nop 0
	v_sub_f32_e32 v130, v130, v131
	v_cvt_pk_bf16_f32 v130, v132, v130
	v_mov_b32_e32 v132, v36
	v_pk_mul_f32 v[132:133], v[132:133], v[160:161]
	s_nop 0
	v_sub_f32_e32 v131, v132, v133
	v_mov_b32_e32 v132, v37
	v_mov_b32_e32 v133, v27
	v_pk_mul_f32 v[132:133], v[132:133], v[154:155]
	s_nop 0
	v_sub_f32_e32 v132, v132, v133
	v_cvt_pk_bf16_f32 v131, v131, v132
	v_mov_b32_e32 v132, v24
	v_mov_b32_e32 v133, v34
	v_pk_mul_f32 v[132:133], v[132:133], v[150:151]
	v_mov_b32_e32 v150, v26
	v_add_f32_e32 v147, v133, v132
	v_mov_b32_e32 v132, v25
	v_mov_b32_e32 v133, v35
	v_mov_b32_e32 v151, v36
	v_pk_mul_f32 v[132:133], v[132:133], v[152:153]
	v_pk_mul_f32 v[150:151], v[150:151], v[160:161]
	v_add_f32_e32 v132, v133, v132
	v_add_f32_e32 v133, v151, v150
	v_mov_b32_e32 v150, v27
	v_mov_b32_e32 v151, v37
	v_pk_mul_f32 v[150:151], v[150:151], v[154:155]
	v_cvt_pk_bf16_f32 v132, v147, v132
	s_nop 0
	v_add_f32_e32 v147, v151, v150
	v_cvt_pk_bf16_f32 v133, v133, v147
	global_store_dwordx4 v[162:163], v[130:133], off offset:256 sc1
	v_mov_b32_e32 v162, v30
	v_mov_b32_e32 v163, v40
	v_add_u32_e32 v130, 0xa0, v144
	v_lshrrev_b32_e32 v131, 6, v130
	v_cndmask_b32_e64 v130, v130, v131, s[40:41]
	v_lshlrev_b32_e32 v130, 5, v130
	v_and_b32_e32 v130, 0x7e0, v130
	v_add_lshl_u32 v130, v130, v145, 1
	v_ashrrev_i32_e32 v131, 31, v130
	v_lshlrev_b32_e32 v150, 2, v130
	v_add_u32_e32 v150, 0x20000, v150
	ds_read_b128 v[130:133], v150 offset:16
	ds_read_b128 v[150:153], v150
	s_waitcnt lgkmcnt(1)
	v_cndmask_b32_e64 v161, v131, 0, vcc
	s_waitcnt lgkmcnt(0)
; __device__ __forceinline__ unsigned cvt_pk_bf16(float lo, float hi) { unsigned r; asm volatile("v_cvt_pk_bf16_f32 %0, %1, %2" : "=v"(r) : "v"(lo), "v"(hi)); return r; }
;     template <int LDC> __device__ __forceinline__ void store_rope(const f32x4 (&acc)[2][2][4][2], bf16_t* base, int row0, int wc, int fq) const {
;         bf16_t* rp = base + (size_t)row0 * LDC; const int axis = wc >> 1, f0 = 16 * (wc & 1) + 4 * fq;
; #pragma unroll
;         for (int ai = 0; ai < 2; ++ai)
; #pragma unroll
;             for (int m = 0; m < 4; ++m) { const int row = row0 + ai * HALF + m * 16; bf16_t* rowp = rp + (size_t)(ai * HALF + m * 16) * LDC;
;                 const int t = row & (SEQ - 1), pos = axis ? (t & 63) : (t >> 6);
;                 f32x4 cs0 = *(const f32x4*)(TAB + (pos * 32 + f0) * 2), cs1 = *(const f32x4*)(TAB + (pos * 32 + f0) * 2 + 4);
;                 if (row >= ML) { cs0 = (f32x4){1.f, 0.f, 1.f, 0.f}; cs1 = cs0; }
; #pragma unroll
;                 for (int bj = 0; bj < 2; ++bj) { const f32x4 x1 = acc[ai][bj][m][0], x2 = acc[ai][bj][m][1];
;                     u32x4 w;
;                     w.x = cvt_pk_bf16(x1[0] * cs0[0] - x2[0] * cs0[1], x1[1] * cs0[2] - x2[1] * cs0[3]);
;                     w.y = cvt_pk_bf16(x1[2] * cs1[0] - x2[2] * cs1[1], x1[3] * cs1[2] - x2[3] * cs1[3]);
;                     w.z = cvt_pk_bf16(x2[0] * cs0[0] + x1[0] * cs0[1], x2[1] * cs0[2] + x1[1] * cs0[3]);
;                     w.w = cvt_pk_bf16(x2[2] * cs1[0] + x1[2] * cs1[1], x2[3] * cs1[2] + x1[3] * cs1[3]);
;                     *(u32x4*)(rowp + bj * HALF) = w; } }
	v_cndmask_b32_e64 v151, v151, 0, vcc
	v_cndmask_b32_e64 v150, v150, 1.0, vcc
	v_cndmask_b32_e64 v160, v130, 1.0, vcc
	v_mov_b32_e32 v130, v38
	v_mov_b32_e32 v131, v28
	v_pk_mul_f32 v[130:131], v[130:131], v[150:151]
	v_cndmask_b32_e64 v153, v153, 0, vcc
	v_cndmask_b32_e64 v152, v152, 1.0, vcc
	v_cndmask_b32_e64 v154, v132, 1.0, vcc
	v_sub_f32_e32 v132, v130, v131
	v_mov_b32_e32 v130, v39
	v_mov_b32_e32 v131, v29
	v_pk_mul_f32 v[130:131], v[130:131], v[152:153]
	v_cndmask_b32_e64 v155, v133, 0, vcc
	v_sub_f32_e32 v130, v130, v131
	v_cvt_pk_bf16_f32 v130, v132, v130
	v_mov_b32_e32 v132, v40
	v_mov_b32_e32 v133, v30
	v_pk_mul_f32 v[132:133], v[132:133], v[160:161]
	v_pk_mul_f32 v[162:163], v[162:163], v[160:161]
	v_sub_f32_e32 v131, v132, v133
	v_mov_b32_e32 v132, v41
	v_mov_b32_e32 v133, v31
	v_pk_mul_f32 v[132:133], v[132:133], v[154:155]
	s_nop 0
	v_sub_f32_e32 v132, v132, v133
	v_cvt_pk_bf16_f32 v131, v131, v132
	v_mov_b32_e32 v132, v28
	v_mov_b32_e32 v133, v38
	v_pk_mul_f32 v[132:133], v[132:133], v[150:151]
	s_nop 0
	v_add_f32_e32 v147, v133, v132
	v_mov_b32_e32 v132, v29
	v_mov_b32_e32 v133, v39
	v_pk_mul_f32 v[132:133], v[132:133], v[152:153]
	s_nop 0
	v_add_f32_e32 v132, v133, v132
	v_add_f32_e32 v133, v163, v162
	v_mov_b32_e32 v162, v31
	v_mov_b32_e32 v163, v41
	v_pk_mul_f32 v[162:163], v[162:163], v[154:155]
	v_cvt_pk_bf16_f32 v132, v147, v132
	s_nop 0
	v_add_f32_e32 v147, v163, v162
	v_add_co_u32_e32 v162, vcc, s18, v148
	v_cvt_pk_bf16_f32 v133, v133, v147
	s_movk_i32 s18, 0x3f4f
	s_nop 0
	v_addc_co_u32_e32 v163, vcc, 0, v149, vcc
	global_store_dwordx4 v[162:163], v[130:133], off sc1
	v_cmp_lt_i32_e32 vcc, s18, v144
	s_mov_b32 s18, 0x57000
	v_mov_b32_e32 v130, v16
	v_mov_b32_e32 v131, v8
	v_pk_mul_f32 v[130:131], v[130:131], v[150:151]
	v_mov_b32_e32 v133, v10
	v_sub_f32_e32 v132, v130, v131
	v_mov_b32_e32 v130, v17
	v_mov_b32_e32 v131, v9
	v_pk_mul_f32 v[130:131], v[130:131], v[152:153]
	s_nop 0
	v_sub_f32_e32 v130, v130, v131
	v_cvt_pk_bf16_f32 v130, v132, v130
	v_mov_b32_e32 v132, v18
	v_pk_mul_f32 v[132:133], v[132:133], v[160:161]
	s_nop 0
	v_sub_f32_e32 v131, v132, v133
	v_mov_b32_e32 v132, v19
	v_mov_b32_e32 v133, v11
	v_pk_mul_f32 v[132:133], v[132:133], v[154:155]
	s_nop 0
	v_sub_f32_e32 v132, v132, v133
	v_cvt_pk_bf16_f32 v131, v131, v132
	v_mov_b32_e32 v132, v8
	v_mov_b32_e32 v133, v16
	v_pk_mul_f32 v[132:133], v[132:133], v[150:151]
	v_mov_b32_e32 v150, v10
	v_add_f32_e32 v147, v133, v132
	v_mov_b32_e32 v132, v9
	v_mov_b32_e32 v133, v17
	v_mov_b32_e32 v151, v18
	v_pk_mul_f32 v[132:133], v[132:133], v[152:153]
	v_pk_mul_f32 v[150:151], v[150:151], v[160:161]
	v_add_f32_e32 v132, v133, v132
	v_add_f32_e32 v133, v151, v150
	v_mov_b32_e32 v150, v11
	v_mov_b32_e32 v151, v19
	v_pk_mul_f32 v[150:151], v[150:151], v[154:155]
	v_cvt_pk_bf16_f32 v132, v147, v132
	s_nop 0
	v_add_f32_e32 v147, v151, v150
	v_cvt_pk_bf16_f32 v133, v133, v147
	global_store_dwordx4 v[162:163], v[130:133], off offset:256 sc1
	v_mov_b32_e32 v162, v14
	v_mov_b32_e32 v163, v22
	v_add_u32_e32 v130, 0xb0, v144
	v_lshrrev_b32_e32 v131, 6, v130
	v_cndmask_b32_e64 v130, v130, v131, s[40:41]
	v_lshlrev_b32_e32 v130, 5, v130
	v_and_b32_e32 v130, 0x7e0, v130
	v_add_lshl_u32 v130, v130, v145, 1
	v_ashrrev_i32_e32 v131, 31, v130
	v_lshlrev_b32_e32 v150, 2, v130
	v_add_u32_e32 v150, 0x20000, v150
	ds_read_b128 v[130:133], v150 offset:16
	ds_read_b128 v[150:153], v150
	s_waitcnt lgkmcnt(1)
	v_cndmask_b32_e64 v161, v131, 0, vcc
	s_waitcnt lgkmcnt(0)
	v_cndmask_b32_e64 v151, v151, 0, vcc
	v_cndmask_b32_e64 v150, v150, 1.0, vcc
	v_cndmask_b32_e64 v160, v130, 1.0, vcc
	v_mov_b32_e32 v130, v20
	v_mov_b32_e32 v131, v12
	v_pk_mul_f32 v[130:131], v[130:131], v[150:151]
	v_cndmask_b32_e64 v153, v153, 0, vcc
	v_cndmask_b32_e64 v152, v152, 1.0, vcc
	v_cndmask_b32_e64 v154, v132, 1.0, vcc
	v_sub_f32_e32 v132, v130, v131
	v_mov_b32_e32 v130, v21
	v_mov_b32_e32 v131, v13
	v_pk_mul_f32 v[130:131], v[130:131], v[152:153]
	v_cndmask_b32_e64 v155, v133, 0, vcc
	v_sub_f32_e32 v130, v130, v131
	v_cvt_pk_bf16_f32 v130, v132, v130
	v_mov_b32_e32 v132, v22
	v_mov_b32_e32 v133, v14
	v_pk_mul_f32 v[132:133], v[132:133], v[160:161]
	v_pk_mul_f32 v[162:163], v[162:163], v[160:161]
	v_sub_f32_e32 v131, v132, v133
	v_mov_b32_e32 v132, v23
	v_mov_b32_e32 v133, v15
	v_pk_mul_f32 v[132:133], v[132:133], v[154:155]
	v_add_co_u32_e32 v148, vcc, s18, v148
	v_sub_f32_e32 v132, v132, v133
	v_cvt_pk_bf16_f32 v131, v131, v132
	v_mov_b32_e32 v132, v12
	v_mov_b32_e32 v133, v20
	v_pk_mul_f32 v[132:133], v[132:133], v[150:151]
	v_addc_co_u32_e32 v149, vcc, 0, v149, vcc
	v_add_f32_e32 v145, v133, v132
	v_mov_b32_e32 v132, v13
	v_mov_b32_e32 v133, v21
	v_pk_mul_f32 v[132:133], v[132:133], v[152:153]
	s_nop 0
	v_add_f32_e32 v132, v133, v132
	v_add_f32_e32 v133, v163, v162
	v_mov_b32_e32 v162, v15
	v_mov_b32_e32 v163, v23
	v_pk_mul_f32 v[162:163], v[162:163], v[154:155]
	v_cvt_pk_bf16_f32 v132, v145, v132
	s_nop 0
	v_add_f32_e32 v145, v163, v162
	v_cvt_pk_bf16_f32 v133, v133, v145
	global_store_dwordx4 v[148:149], v[130:133], off sc1
	s_nop 1
	v_mov_b32_e32 v130, v4
	v_mov_b32_e32 v131, v0
	v_pk_mul_f32 v[130:131], v[130:131], v[150:151]
	v_mov_b32_e32 v133, v2
	v_sub_f32_e32 v132, v130, v131
	v_mov_b32_e32 v130, v5
	v_mov_b32_e32 v131, v1
	v_pk_mul_f32 v[130:131], v[130:131], v[152:153]
	s_nop 0
	v_sub_f32_e32 v130, v130, v131
	v_cvt_pk_bf16_f32 v130, v132, v130
	v_mov_b32_e32 v132, v6
	v_pk_mul_f32 v[132:133], v[132:133], v[160:161]
	s_nop 0
	v_sub_f32_e32 v131, v132, v133
	v_mov_b32_e32 v132, v7
	v_mov_b32_e32 v133, v3
	v_pk_mul_f32 v[132:133], v[132:133], v[154:155]
	s_nop 0
	v_sub_f32_e32 v132, v132, v133
	v_cvt_pk_bf16_f32 v131, v131, v132
	v_mov_b32_e32 v132, v0
	v_mov_b32_e32 v133, v4
	v_pk_mul_f32 v[132:133], v[132:133], v[150:151]
	v_mov_b32_e32 v150, v2
	v_add_f32_e32 v145, v133, v132
	v_mov_b32_e32 v132, v1
	v_mov_b32_e32 v133, v5
	v_mov_b32_e32 v151, v6
	v_pk_mul_f32 v[132:133], v[132:133], v[152:153]
	v_pk_mul_f32 v[150:151], v[150:151], v[160:161]
	v_add_f32_e32 v132, v133, v132
	v_add_f32_e32 v133, v151, v150
	v_mov_b32_e32 v150, v3
	v_mov_b32_e32 v151, v7
	v_pk_mul_f32 v[150:151], v[150:151], v[154:155]
	v_cvt_pk_bf16_f32 v132, v145, v132
	s_nop 0
	v_add_f32_e32 v145, v151, v150
	v_cvt_pk_bf16_f32 v133, v133, v145
	global_store_dwordx4 v[148:149], v[130:133], off offset:256 sc1
